# v20 + K-loop tail pointer increments hoisted ahead of the last load-segment wait (back-edge rotation, sec 7.11) in all 9 GEMM loops
# speedup vs baseline: 1.0101x; 1.0083x over previous
.LBB0_293:
	s_add_i32 s43, s28, 2
	s_add_u32 s53, s40, 0x80
	s_addc_u32 s29, s41, 0
	s_add_i32 s72, 0, 0x10000
	s_cmp_eq_u32 s49, s28
	s_cselect_b32 s29, s61, s29
	s_cselect_b32 s28, s60, s53
	v_add_u32_e32 v128, s72, v181
	s_cselect_b32 s71, s65, s42
	s_cselect_b32 s70, s64, s33
	s_add_i32 s53, 0, 0x14000
	ds_read_b128 v[130:133], v128
	ds_read_b128 v[134:137], v128 offset:1024
	ds_read_b128 v[138:141], v128 offset:2048
	ds_read_b128 v[142:145], v128 offset:3072
	v_add_u32_e32 v128, s53, v181
	s_waitcnt lgkmcnt(0)
	ds_read_b128 v[162:165], v128
	ds_read_b128 v[166:169], v128 offset:1024
	ds_read_b128 v[170:173], v128 offset:2048
	ds_read_b128 v[174:177], v128 offset:3072
	v_lshl_add_u64 v[178:179], s[40:41], 0, v[158:159]
	s_add_i32 m0, s90, 0xc000
	ds_read_b128 v[186:189], v183
	ds_read_b128 v[190:193], v183 offset:1024
	ds_read_b128 v[194:197], v183 offset:2048
	ds_read_b128 v[198:201], v183 offset:3072
	ds_read_b128 v[202:205], v183 offset:4096
	ds_read_b128 v[206:209], v183 offset:5120
	ds_read_b128 v[210:213], v183 offset:6144
	ds_read_b128 v[214:217], v183 offset:7168
	global_load_lds_dwordx4 v[178:179], off
	v_lshl_add_u64 v[178:179], s[40:41], 0, v[160:161]
	s_add_i32 m0, s90, 0xe000
	s_nop 0
	global_load_lds_dwordx4 v[178:179], off
	s_waitcnt vmcnt(8)
	s_waitcnt lgkmcnt(0)
	s_barrier
	s_waitcnt lgkmcnt(0)
	v_mfma_f32_16x16x32_bf16 v[112:115], v[130:133], v[186:189], v[112:115]
	v_mfma_f32_16x16x32_bf16 v[120:123], v[138:141], v[186:189], v[120:123]
	v_mfma_f32_16x16x32_bf16 v[96:99], v[130:133], v[194:197], v[96:99]
	v_mfma_f32_16x16x32_bf16 v[104:107], v[138:141], v[194:197], v[104:107]
	v_mfma_f32_16x16x32_bf16 v[80:83], v[130:133], v[202:205], v[80:83]
	v_mfma_f32_16x16x32_bf16 v[88:91], v[138:141], v[202:205], v[88:91]
	v_mfma_f32_16x16x32_bf16 v[64:67], v[130:133], v[210:213], v[64:67]
	v_mfma_f32_16x16x32_bf16 v[72:75], v[138:141], v[210:213], v[72:75]
	v_mfma_f32_16x16x32_bf16 v[112:115], v[134:137], v[190:193], v[112:115]
	v_mfma_f32_16x16x32_bf16 v[120:123], v[142:145], v[190:193], v[120:123]
	v_mfma_f32_16x16x32_bf16 v[96:99], v[134:137], v[198:201], v[96:99]
	v_mfma_f32_16x16x32_bf16 v[104:107], v[142:145], v[198:201], v[104:107]
	v_mfma_f32_16x16x32_bf16 v[80:83], v[134:137], v[206:209], v[80:83]
	v_mfma_f32_16x16x32_bf16 v[88:91], v[142:145], v[206:209], v[88:91]
	v_mfma_f32_16x16x32_bf16 v[64:67], v[134:137], v[214:217], v[64:67]
	v_mfma_f32_16x16x32_bf16 v[72:75], v[142:145], v[214:217], v[72:75]
	v_mfma_f32_16x16x32_bf16 v[116:119], v[162:165], v[186:189], v[116:119]
	v_mfma_f32_16x16x32_bf16 v[124:127], v[170:173], v[186:189], v[124:127]
	v_mfma_f32_16x16x32_bf16 v[100:103], v[162:165], v[194:197], v[100:103]
	v_mfma_f32_16x16x32_bf16 v[108:111], v[170:173], v[194:197], v[108:111]
	v_mfma_f32_16x16x32_bf16 v[84:87], v[162:165], v[202:205], v[84:87]
	v_mfma_f32_16x16x32_bf16 v[92:95], v[170:173], v[202:205], v[92:95]
	v_mfma_f32_16x16x32_bf16 v[68:71], v[162:165], v[210:213], v[68:71]
	v_mfma_f32_16x16x32_bf16 v[76:79], v[170:173], v[210:213], v[76:79]
	v_mfma_f32_16x16x32_bf16 v[116:119], v[166:169], v[190:193], v[116:119]
	v_mfma_f32_16x16x32_bf16 v[124:127], v[174:177], v[190:193], v[124:127]
	v_mfma_f32_16x16x32_bf16 v[100:103], v[166:169], v[198:201], v[100:103]
	v_mfma_f32_16x16x32_bf16 v[108:111], v[174:177], v[198:201], v[108:111]
	v_mfma_f32_16x16x32_bf16 v[84:87], v[166:169], v[206:209], v[84:87]
	v_mfma_f32_16x16x32_bf16 v[92:95], v[174:177], v[206:209], v[92:95]
	v_mfma_f32_16x16x32_bf16 v[68:71], v[166:169], v[214:217], v[68:71]
	v_mfma_f32_16x16x32_bf16 v[76:79], v[174:177], v[214:217], v[76:79]
	s_barrier
	s_add_i32 s72, s72, s87
	v_lshl_add_u64 v[178:179], s[70:71], 0, v[150:151]
	s_mov_b32 m0, s72
	ds_read_b128 v[186:189], v183 offset:16384
	ds_read_b128 v[190:193], v183 offset:17408
	ds_read_b128 v[194:197], v183 offset:18432
	ds_read_b128 v[198:201], v183 offset:19456
	ds_read_b128 v[202:205], v183 offset:20480
	ds_read_b128 v[206:209], v183 offset:21504
	ds_read_b128 v[210:213], v183 offset:22528
	ds_read_b128 v[214:217], v183 offset:23552
	global_load_lds_dwordx4 v[178:179], off
	s_add_i32 m0, s72, 0x2000
	v_lshl_add_u64 v[218:219], s[70:71], 0, v[154:155]
	s_add_u32 s70, s70, s14
	s_addc_u32 s71, s71, s15
	s_add_i32 s53, s53, s87
	global_load_lds_dwordx4 v[218:219], off
	v_lshl_add_u64 v[220:221], s[70:71], 0, v[150:151]
	s_mov_b32 m0, s53
	v_lshl_add_u64 v[222:223], s[70:71], 0, v[154:155]
	global_load_lds_dwordx4 v[220:221], off
	s_add_i32 m0, s53, 0x2000
	v_lshl_add_u64 v[224:225], s[28:29], 0, v[148:149]
	global_load_lds_dwordx4 v[222:223], off
	s_mov_b32 m0, s90
	v_lshl_add_u64 v[226:227], s[28:29], 0, v[152:153]
	global_load_lds_dwordx4 v[224:225], off
	s_mov_b32 m0, s91
	s_nop 0
	global_load_lds_dwordx4 v[226:227], off
	s_waitcnt vmcnt(8)
	s_waitcnt lgkmcnt(0)
	s_barrier
	s_waitcnt lgkmcnt(0)
	v_mfma_f32_16x16x32_bf16 v[48:51], v[130:133], v[186:189], v[48:51]
	v_mfma_f32_16x16x32_bf16 v[56:59], v[138:141], v[186:189], v[56:59]
	v_mfma_f32_16x16x32_bf16 v[32:35], v[130:133], v[194:197], v[32:35]
	v_mfma_f32_16x16x32_bf16 v[40:43], v[138:141], v[194:197], v[40:43]
	v_mfma_f32_16x16x32_bf16 v[16:19], v[130:133], v[202:205], v[16:19]
	v_mfma_f32_16x16x32_bf16 v[24:27], v[138:141], v[202:205], v[24:27]
	v_mfma_f32_16x16x32_bf16 v[0:3], v[130:133], v[210:213], v[0:3]
	v_mfma_f32_16x16x32_bf16 v[12:15], v[138:141], v[210:213], v[12:15]
	v_mfma_f32_16x16x32_bf16 v[48:51], v[134:137], v[190:193], v[48:51]
	v_mfma_f32_16x16x32_bf16 v[56:59], v[142:145], v[190:193], v[56:59]
	v_mfma_f32_16x16x32_bf16 v[32:35], v[134:137], v[198:201], v[32:35]
	v_mfma_f32_16x16x32_bf16 v[40:43], v[142:145], v[198:201], v[40:43]
	v_mfma_f32_16x16x32_bf16 v[16:19], v[134:137], v[206:209], v[16:19]
	v_mfma_f32_16x16x32_bf16 v[24:27], v[142:145], v[206:209], v[24:27]
	v_mfma_f32_16x16x32_bf16 v[0:3], v[134:137], v[214:217], v[0:3]
	v_mfma_f32_16x16x32_bf16 v[12:15], v[142:145], v[214:217], v[12:15]
	v_mfma_f32_16x16x32_bf16 v[52:55], v[162:165], v[186:189], v[52:55]
	v_mfma_f32_16x16x32_bf16 v[60:63], v[170:173], v[186:189], v[60:63]
	v_mfma_f32_16x16x32_bf16 v[36:39], v[162:165], v[194:197], v[36:39]
	v_mfma_f32_16x16x32_bf16 v[44:47], v[170:173], v[194:197], v[44:47]
	v_mfma_f32_16x16x32_bf16 v[20:23], v[162:165], v[202:205], v[20:23]
	v_mfma_f32_16x16x32_bf16 v[28:31], v[170:173], v[202:205], v[28:31]
	v_mfma_f32_16x16x32_bf16 v[4:7], v[162:165], v[210:213], v[4:7]
	v_mfma_f32_16x16x32_bf16 v[8:11], v[170:173], v[210:213], v[8:11]
	v_mfma_f32_16x16x32_bf16 v[52:55], v[166:169], v[190:193], v[52:55]
	v_mfma_f32_16x16x32_bf16 v[60:63], v[174:177], v[190:193], v[60:63]
	v_mfma_f32_16x16x32_bf16 v[36:39], v[166:169], v[198:201], v[36:39]
	v_mfma_f32_16x16x32_bf16 v[44:47], v[174:177], v[198:201], v[44:47]
	v_mfma_f32_16x16x32_bf16 v[20:23], v[166:169], v[206:209], v[20:23]
	v_mfma_f32_16x16x32_bf16 v[28:31], v[174:177], v[206:209], v[28:31]
	v_mfma_f32_16x16x32_bf16 v[4:7], v[166:169], v[214:217], v[4:7]
	v_mfma_f32_16x16x32_bf16 v[8:11], v[174:177], v[214:217], v[8:11]
	s_barrier
	s_add_i32 s53, 0, 0x18000
	v_add_u32_e32 v128, s53, v181
	s_add_i32 s70, 0, 0x1c000
	ds_read_b128 v[130:133], v128
	ds_read_b128 v[134:137], v128 offset:1024
	ds_read_b128 v[138:141], v128 offset:2048
	ds_read_b128 v[142:145], v128 offset:3072
	v_add_u32_e32 v128, s70, v181
	ds_read_b128 v[162:165], v128
	ds_read_b128 v[166:169], v128 offset:1024
	ds_read_b128 v[170:173], v128 offset:2048
	ds_read_b128 v[174:177], v128 offset:3072
	s_add_u32 s28, s28, s14
	s_addc_u32 s29, s29, s15
	s_mov_b32 m0, s92
	v_lshl_add_u64 v[228:229], s[28:29], 0, v[148:149]
	ds_read_b128 v[186:189], v183 offset:32768
	ds_read_b128 v[190:193], v183 offset:33792
	ds_read_b128 v[194:197], v183 offset:34816
	ds_read_b128 v[198:201], v183 offset:35840
	ds_read_b128 v[202:205], v183 offset:36864
	ds_read_b128 v[206:209], v183 offset:37888
	ds_read_b128 v[210:213], v183 offset:38912
	ds_read_b128 v[214:217], v183 offset:39936
	global_load_lds_dwordx4 v[228:229], off
	v_lshl_add_u64 v[228:229], s[28:29], 0, v[152:153]
	s_mov_b32 m0, s93
	s_nop 0
	global_load_lds_dwordx4 v[228:229], off
	s_waitcnt vmcnt(8)
	s_waitcnt lgkmcnt(0)
	s_barrier
	s_waitcnt lgkmcnt(0)
	v_mfma_f32_16x16x32_bf16 v[112:115], v[130:133], v[186:189], v[112:115]
	v_mfma_f32_16x16x32_bf16 v[120:123], v[138:141], v[186:189], v[120:123]
	v_mfma_f32_16x16x32_bf16 v[96:99], v[130:133], v[194:197], v[96:99]
	v_mfma_f32_16x16x32_bf16 v[104:107], v[138:141], v[194:197], v[104:107]
	v_mfma_f32_16x16x32_bf16 v[80:83], v[130:133], v[202:205], v[80:83]
	v_mfma_f32_16x16x32_bf16 v[88:91], v[138:141], v[202:205], v[88:91]
	v_mfma_f32_16x16x32_bf16 v[64:67], v[130:133], v[210:213], v[64:67]
	v_mfma_f32_16x16x32_bf16 v[72:75], v[138:141], v[210:213], v[72:75]
	v_mfma_f32_16x16x32_bf16 v[112:115], v[134:137], v[190:193], v[112:115]
	v_mfma_f32_16x16x32_bf16 v[120:123], v[142:145], v[190:193], v[120:123]
	v_mfma_f32_16x16x32_bf16 v[96:99], v[134:137], v[198:201], v[96:99]
	v_mfma_f32_16x16x32_bf16 v[104:107], v[142:145], v[198:201], v[104:107]
	v_mfma_f32_16x16x32_bf16 v[80:83], v[134:137], v[206:209], v[80:83]
	v_mfma_f32_16x16x32_bf16 v[88:91], v[142:145], v[206:209], v[88:91]
	v_mfma_f32_16x16x32_bf16 v[64:67], v[134:137], v[214:217], v[64:67]
	v_mfma_f32_16x16x32_bf16 v[72:75], v[142:145], v[214:217], v[72:75]
	v_mfma_f32_16x16x32_bf16 v[116:119], v[162:165], v[186:189], v[116:119]
	v_mfma_f32_16x16x32_bf16 v[124:127], v[170:173], v[186:189], v[124:127]
	v_mfma_f32_16x16x32_bf16 v[100:103], v[162:165], v[194:197], v[100:103]
	v_mfma_f32_16x16x32_bf16 v[108:111], v[170:173], v[194:197], v[108:111]
	v_mfma_f32_16x16x32_bf16 v[84:87], v[162:165], v[202:205], v[84:87]
	v_mfma_f32_16x16x32_bf16 v[92:95], v[170:173], v[202:205], v[92:95]
	v_mfma_f32_16x16x32_bf16 v[68:71], v[162:165], v[210:213], v[68:71]
	v_mfma_f32_16x16x32_bf16 v[76:79], v[170:173], v[210:213], v[76:79]
	v_mfma_f32_16x16x32_bf16 v[116:119], v[166:169], v[190:193], v[116:119]
	v_mfma_f32_16x16x32_bf16 v[124:127], v[174:177], v[190:193], v[124:127]
	v_mfma_f32_16x16x32_bf16 v[100:103], v[166:169], v[198:201], v[100:103]
	v_mfma_f32_16x16x32_bf16 v[108:111], v[174:177], v[198:201], v[108:111]
	v_mfma_f32_16x16x32_bf16 v[84:87], v[166:169], v[206:209], v[84:87]
	v_mfma_f32_16x16x32_bf16 v[92:95], v[174:177], v[206:209], v[92:95]
	v_mfma_f32_16x16x32_bf16 v[68:71], v[166:169], v[214:217], v[68:71]
	v_mfma_f32_16x16x32_bf16 v[76:79], v[174:177], v[214:217], v[76:79]
	s_barrier
	s_add_i32 s28, s53, s87
	v_lshl_add_u64 v[178:179], v[178:179], 0, s[34:35]
	s_mov_b32 m0, s28
	ds_read_b128 v[186:189], v183 offset:49152
	ds_read_b128 v[190:193], v183 offset:50176
	ds_read_b128 v[194:197], v183 offset:51200
	ds_read_b128 v[198:201], v183 offset:52224
	ds_read_b128 v[202:205], v183 offset:53248
	ds_read_b128 v[206:209], v183 offset:54272
	ds_read_b128 v[210:213], v183 offset:55296
	ds_read_b128 v[214:217], v183 offset:56320
	global_load_lds_dwordx4 v[178:179], off
	v_lshl_add_u64 v[178:179], v[218:219], 0, s[34:35]
	s_add_i32 m0, s28, 0x2000
	s_add_i32 s28, s70, s87
	global_load_lds_dwordx4 v[178:179], off
	v_lshl_add_u64 v[178:179], v[220:221], 0, s[34:35]
	s_mov_b32 m0, s28
	s_nop 0
	global_load_lds_dwordx4 v[178:179], off
	v_lshl_add_u64 v[178:179], v[222:223], 0, s[34:35]
	s_add_i32 m0, s28, 0x2000
	s_nop 0
	global_load_lds_dwordx4 v[178:179], off
	v_lshl_add_u64 v[178:179], v[224:225], 0, s[34:35]
	s_mov_b32 m0, s97
	s_nop 0
	global_load_lds_dwordx4 v[178:179], off
	v_lshl_add_u64 v[178:179], v[226:227], 0, s[34:35]
	s_mov_b32 m0, s48
	s_nop 0
	global_load_lds_dwordx4 v[178:179], off
	s_add_u32 s40, s40, 0x100
	s_addc_u32 s41, s41, 0
	s_add_u32 s33, s33, 0x100
	s_addc_u32 s42, s42, 0
	s_waitcnt vmcnt(8)
	s_waitcnt lgkmcnt(0)
	s_barrier
	s_waitcnt lgkmcnt(0)
	v_mfma_f32_16x16x32_bf16 v[48:51], v[130:133], v[186:189], v[48:51]
	v_mfma_f32_16x16x32_bf16 v[56:59], v[138:141], v[186:189], v[56:59]
	v_mfma_f32_16x16x32_bf16 v[32:35], v[130:133], v[194:197], v[32:35]
	v_mfma_f32_16x16x32_bf16 v[40:43], v[138:141], v[194:197], v[40:43]
	v_mfma_f32_16x16x32_bf16 v[16:19], v[130:133], v[202:205], v[16:19]
	v_mfma_f32_16x16x32_bf16 v[24:27], v[138:141], v[202:205], v[24:27]
	v_mfma_f32_16x16x32_bf16 v[0:3], v[130:133], v[210:213], v[0:3]
	v_mfma_f32_16x16x32_bf16 v[12:15], v[138:141], v[210:213], v[12:15]
	v_mfma_f32_16x16x32_bf16 v[48:51], v[134:137], v[190:193], v[48:51]
	v_mfma_f32_16x16x32_bf16 v[56:59], v[142:145], v[190:193], v[56:59]
	v_mfma_f32_16x16x32_bf16 v[32:35], v[134:137], v[198:201], v[32:35]
	v_mfma_f32_16x16x32_bf16 v[40:43], v[142:145], v[198:201], v[40:43]
	v_mfma_f32_16x16x32_bf16 v[16:19], v[134:137], v[206:209], v[16:19]
	v_mfma_f32_16x16x32_bf16 v[24:27], v[142:145], v[206:209], v[24:27]
	v_mfma_f32_16x16x32_bf16 v[0:3], v[134:137], v[214:217], v[0:3]
	v_mfma_f32_16x16x32_bf16 v[12:15], v[142:145], v[214:217], v[12:15]
	v_mfma_f32_16x16x32_bf16 v[52:55], v[162:165], v[186:189], v[52:55]
	v_mfma_f32_16x16x32_bf16 v[60:63], v[170:173], v[186:189], v[60:63]
	v_mfma_f32_16x16x32_bf16 v[36:39], v[162:165], v[194:197], v[36:39]
	v_mfma_f32_16x16x32_bf16 v[44:47], v[170:173], v[194:197], v[44:47]
	v_mfma_f32_16x16x32_bf16 v[20:23], v[162:165], v[202:205], v[20:23]
	v_mfma_f32_16x16x32_bf16 v[28:31], v[170:173], v[202:205], v[28:31]
	v_mfma_f32_16x16x32_bf16 v[4:7], v[162:165], v[210:213], v[4:7]
	v_mfma_f32_16x16x32_bf16 v[8:11], v[170:173], v[210:213], v[8:11]
	v_mfma_f32_16x16x32_bf16 v[52:55], v[166:169], v[190:193], v[52:55]
	v_mfma_f32_16x16x32_bf16 v[60:63], v[174:177], v[190:193], v[60:63]
	v_mfma_f32_16x16x32_bf16 v[36:39], v[166:169], v[198:201], v[36:39]
	v_mfma_f32_16x16x32_bf16 v[44:47], v[174:177], v[198:201], v[44:47]
	v_mfma_f32_16x16x32_bf16 v[20:23], v[166:169], v[206:209], v[20:23]
	v_mfma_f32_16x16x32_bf16 v[28:31], v[174:177], v[206:209], v[28:31]
	v_mfma_f32_16x16x32_bf16 v[4:7], v[166:169], v[214:217], v[4:7]
	v_mfma_f32_16x16x32_bf16 v[8:11], v[174:177], v[214:217], v[8:11]
	s_barrier
	s_cmp_ge_i32 s43, s95
	s_mov_b32 s28, s43
	s_cbranch_scc0 .LBB0_293

.Lrx_join_764_1:
	s_mov_b32 s101, 0
	s_waitcnt lgkmcnt(0)
	s_barrier
	s_waitcnt lgkmcnt(0)
	v_mfma_f32_16x16x32_bf16 v[60:63], v[152:155], v[184:187], v[60:63]
	v_mfma_f32_16x16x32_bf16 v[56:59], v[160:163], v[184:187], v[56:59]
	v_mfma_f32_16x16x32_bf16 v[44:47], v[152:155], v[192:195], v[44:47]
	v_mfma_f32_16x16x32_bf16 v[40:43], v[160:163], v[192:195], v[40:43]
	v_mfma_f32_16x16x32_bf16 v[28:31], v[152:155], v[200:203], v[28:31]
	v_mfma_f32_16x16x32_bf16 v[24:27], v[160:163], v[200:203], v[24:27]
	v_mfma_f32_16x16x32_bf16 v[12:15], v[152:155], v[208:211], v[12:15]
	v_mfma_f32_16x16x32_bf16 v[8:11], v[160:163], v[208:211], v[8:11]
	v_mfma_f32_16x16x32_bf16 v[60:63], v[156:159], v[188:191], v[60:63]
	v_mfma_f32_16x16x32_bf16 v[56:59], v[164:167], v[188:191], v[56:59]
	v_mfma_f32_16x16x32_bf16 v[44:47], v[156:159], v[196:199], v[44:47]
	v_mfma_f32_16x16x32_bf16 v[40:43], v[164:167], v[196:199], v[40:43]
	v_mfma_f32_16x16x32_bf16 v[28:31], v[156:159], v[204:207], v[28:31]
	v_mfma_f32_16x16x32_bf16 v[24:27], v[164:167], v[204:207], v[24:27]
	v_mfma_f32_16x16x32_bf16 v[12:15], v[156:159], v[212:215], v[12:15]
	v_mfma_f32_16x16x32_bf16 v[8:11], v[164:167], v[212:215], v[8:11]
	v_mfma_f32_16x16x32_bf16 v[52:55], v[168:171], v[184:187], v[52:55]
	v_mfma_f32_16x16x32_bf16 v[48:51], v[176:179], v[184:187], v[48:51]
	v_mfma_f32_16x16x32_bf16 v[36:39], v[168:171], v[192:195], v[36:39]
	v_mfma_f32_16x16x32_bf16 v[32:35], v[176:179], v[192:195], v[32:35]
	v_mfma_f32_16x16x32_bf16 v[20:23], v[168:171], v[200:203], v[20:23]
	v_mfma_f32_16x16x32_bf16 v[16:19], v[176:179], v[200:203], v[16:19]
	v_mfma_f32_16x16x32_bf16 v[4:7], v[168:171], v[208:211], v[4:7]
	v_mfma_f32_16x16x32_bf16 v[0:3], v[176:179], v[208:211], v[0:3]
	v_mfma_f32_16x16x32_bf16 v[52:55], v[172:175], v[188:191], v[52:55]
	v_mfma_f32_16x16x32_bf16 v[48:51], v[180:183], v[188:191], v[48:51]
	v_mfma_f32_16x16x32_bf16 v[36:39], v[172:175], v[196:199], v[36:39]
	v_mfma_f32_16x16x32_bf16 v[32:35], v[180:183], v[196:199], v[32:35]
	v_mfma_f32_16x16x32_bf16 v[20:23], v[172:175], v[204:207], v[20:23]
	v_mfma_f32_16x16x32_bf16 v[16:19], v[180:183], v[204:207], v[16:19]
	v_mfma_f32_16x16x32_bf16 v[4:7], v[172:175], v[212:215], v[4:7]
	v_mfma_f32_16x16x32_bf16 v[0:3], v[180:183], v[212:215], v[0:3]
	s_barrier
	s_add_i32 s73, 0, 0x18000
	v_add_u32_e32 v128, s73, v149
	s_add_i32 s76, 0, 0x1c000
	ds_read_b128 v[152:155], v128
	ds_read_b128 v[156:159], v128 offset:1024
	ds_read_b128 v[160:163], v128 offset:2048
	ds_read_b128 v[164:167], v128 offset:3072
	v_add_u32_e32 v128, s76, v149
	ds_read_b128 v[168:171], v128
	ds_read_b128 v[172:175], v128 offset:1024
	ds_read_b128 v[176:179], v128 offset:2048
	ds_read_b128 v[180:183], v128 offset:3072
	s_add_u32 s28, s28, s22
	s_addc_u32 s29, s29, s23
	s_mov_b32 m0, s49
	v_lshl_add_u64 v[226:227], s[28:29], 0, v[130:131]
	ds_read_b128 v[184:187], v151 offset:32768
	ds_read_b128 v[188:191], v151 offset:33792
	ds_read_b128 v[192:195], v151 offset:34816
	ds_read_b128 v[196:199], v151 offset:35840
	ds_read_b128 v[200:203], v151 offset:36864
	ds_read_b128 v[204:207], v151 offset:37888
	ds_read_b128 v[208:211], v151 offset:38912
	ds_read_b128 v[212:215], v151 offset:39936
	global_load_lds_dwordx4 v[226:227], off
	v_lshl_add_u64 v[226:227], s[28:29], 0, v[134:135]
	s_mov_b32 m0, s52
	s_nop 0
	global_load_lds_dwordx4 v[226:227], off
	s_waitcnt vmcnt(8)
	s_waitcnt lgkmcnt(0)
	s_barrier
	s_waitcnt lgkmcnt(0)
	v_mfma_f32_16x16x32_bf16 v[120:123], v[152:155], v[184:187], v[120:123]
	v_mfma_f32_16x16x32_bf16 v[124:127], v[160:163], v[184:187], v[124:127]
	v_mfma_f32_16x16x32_bf16 v[108:111], v[152:155], v[192:195], v[108:111]
	v_mfma_f32_16x16x32_bf16 v[104:107], v[160:163], v[192:195], v[104:107]
	v_mfma_f32_16x16x32_bf16 v[92:95], v[152:155], v[200:203], v[92:95]
	v_mfma_f32_16x16x32_bf16 v[88:91], v[160:163], v[200:203], v[88:91]
	v_mfma_f32_16x16x32_bf16 v[76:79], v[152:155], v[208:211], v[76:79]
	v_mfma_f32_16x16x32_bf16 v[72:75], v[160:163], v[208:211], v[72:75]
	v_mfma_f32_16x16x32_bf16 v[120:123], v[156:159], v[188:191], v[120:123]
	v_mfma_f32_16x16x32_bf16 v[124:127], v[164:167], v[188:191], v[124:127]
	v_mfma_f32_16x16x32_bf16 v[108:111], v[156:159], v[196:199], v[108:111]
	v_mfma_f32_16x16x32_bf16 v[104:107], v[164:167], v[196:199], v[104:107]
	v_mfma_f32_16x16x32_bf16 v[92:95], v[156:159], v[204:207], v[92:95]
	v_mfma_f32_16x16x32_bf16 v[88:91], v[164:167], v[204:207], v[88:91]
	v_mfma_f32_16x16x32_bf16 v[76:79], v[156:159], v[212:215], v[76:79]
	v_mfma_f32_16x16x32_bf16 v[72:75], v[164:167], v[212:215], v[72:75]
	v_mfma_f32_16x16x32_bf16 v[116:119], v[168:171], v[184:187], v[116:119]
	v_mfma_f32_16x16x32_bf16 v[112:115], v[176:179], v[184:187], v[112:115]
	v_mfma_f32_16x16x32_bf16 v[100:103], v[168:171], v[192:195], v[100:103]
	v_mfma_f32_16x16x32_bf16 v[96:99], v[176:179], v[192:195], v[96:99]
	v_mfma_f32_16x16x32_bf16 v[84:87], v[168:171], v[200:203], v[84:87]
	v_mfma_f32_16x16x32_bf16 v[80:83], v[176:179], v[200:203], v[80:83]
	v_mfma_f32_16x16x32_bf16 v[68:71], v[168:171], v[208:211], v[68:71]
	v_mfma_f32_16x16x32_bf16 v[64:67], v[176:179], v[208:211], v[64:67]
	v_mfma_f32_16x16x32_bf16 v[116:119], v[172:175], v[188:191], v[116:119]
	v_mfma_f32_16x16x32_bf16 v[112:115], v[180:183], v[188:191], v[112:115]
	v_mfma_f32_16x16x32_bf16 v[100:103], v[172:175], v[196:199], v[100:103]
	v_mfma_f32_16x16x32_bf16 v[96:99], v[180:183], v[196:199], v[96:99]
	v_mfma_f32_16x16x32_bf16 v[84:87], v[172:175], v[204:207], v[84:87]
	v_mfma_f32_16x16x32_bf16 v[80:83], v[180:183], v[204:207], v[80:83]
	v_mfma_f32_16x16x32_bf16 v[68:71], v[172:175], v[212:215], v[68:71]
	v_mfma_f32_16x16x32_bf16 v[64:67], v[180:183], v[212:215], v[64:67]
	s_barrier
	s_add_i32 s28, s73, s18
	v_lshl_add_u64 v[142:143], v[142:143], 0, s[34:35]
	s_mov_b32 m0, s28
	ds_read_b128 v[184:187], v151 offset:49152
	ds_read_b128 v[188:191], v151 offset:50176
	ds_read_b128 v[192:195], v151 offset:51200
	ds_read_b128 v[196:199], v151 offset:52224
	ds_read_b128 v[200:203], v151 offset:53248
	ds_read_b128 v[204:207], v151 offset:54272
	ds_read_b128 v[208:211], v151 offset:55296
	ds_read_b128 v[212:215], v151 offset:56320
	global_load_lds_dwordx4 v[142:143], off
	v_lshl_add_u64 v[142:143], v[216:217], 0, s[34:35]
	s_add_i32 m0, s28, 0x2000
	s_add_i32 s28, s76, s18
	global_load_lds_dwordx4 v[142:143], off
	v_lshl_add_u64 v[142:143], v[218:219], 0, s[34:35]
	s_mov_b32 m0, s28
	s_nop 0
	global_load_lds_dwordx4 v[142:143], off
	v_lshl_add_u64 v[142:143], v[220:221], 0, s[34:35]
	s_add_i32 m0, s28, 0x2000
	s_nop 0
	global_load_lds_dwordx4 v[142:143], off
	v_lshl_add_u64 v[142:143], v[222:223], 0, s[34:35]
	s_mov_b32 m0, s53
	s_nop 0
	global_load_lds_dwordx4 v[142:143], off
	v_lshl_add_u64 v[142:143], v[224:225], 0, s[34:35]
	s_mov_b32 m0, s56
	s_nop 0
	global_load_lds_dwordx4 v[142:143], off
	s_add_u32 s50, s50, 0x100
	s_addc_u32 s51, s51, 0
	s_add_u32 s33, s33, 0x100
	s_addc_u32 s71, s71, 0
	s_waitcnt vmcnt(8)
	s_waitcnt lgkmcnt(0)
	s_barrier
	s_waitcnt lgkmcnt(0)
	v_mfma_f32_16x16x32_bf16 v[60:63], v[152:155], v[184:187], v[60:63]
	v_mfma_f32_16x16x32_bf16 v[56:59], v[160:163], v[184:187], v[56:59]
	v_mfma_f32_16x16x32_bf16 v[44:47], v[152:155], v[192:195], v[44:47]
	v_mfma_f32_16x16x32_bf16 v[40:43], v[160:163], v[192:195], v[40:43]
	v_mfma_f32_16x16x32_bf16 v[28:31], v[152:155], v[200:203], v[28:31]
	v_mfma_f32_16x16x32_bf16 v[24:27], v[160:163], v[200:203], v[24:27]
	v_mfma_f32_16x16x32_bf16 v[12:15], v[152:155], v[208:211], v[12:15]
	v_mfma_f32_16x16x32_bf16 v[8:11], v[160:163], v[208:211], v[8:11]
	v_mfma_f32_16x16x32_bf16 v[60:63], v[156:159], v[188:191], v[60:63]
	v_mfma_f32_16x16x32_bf16 v[56:59], v[164:167], v[188:191], v[56:59]
	v_mfma_f32_16x16x32_bf16 v[44:47], v[156:159], v[196:199], v[44:47]
	v_mfma_f32_16x16x32_bf16 v[40:43], v[164:167], v[196:199], v[40:43]
	v_mfma_f32_16x16x32_bf16 v[28:31], v[156:159], v[204:207], v[28:31]
	v_mfma_f32_16x16x32_bf16 v[24:27], v[164:167], v[204:207], v[24:27]
	v_mfma_f32_16x16x32_bf16 v[12:15], v[156:159], v[212:215], v[12:15]
	v_mfma_f32_16x16x32_bf16 v[8:11], v[164:167], v[212:215], v[8:11]
	v_mfma_f32_16x16x32_bf16 v[52:55], v[168:171], v[184:187], v[52:55]
	v_mfma_f32_16x16x32_bf16 v[48:51], v[176:179], v[184:187], v[48:51]
	v_mfma_f32_16x16x32_bf16 v[36:39], v[168:171], v[192:195], v[36:39]
	v_mfma_f32_16x16x32_bf16 v[32:35], v[176:179], v[192:195], v[32:35]
	v_mfma_f32_16x16x32_bf16 v[20:23], v[168:171], v[200:203], v[20:23]
	v_mfma_f32_16x16x32_bf16 v[16:19], v[176:179], v[200:203], v[16:19]
	v_mfma_f32_16x16x32_bf16 v[4:7], v[168:171], v[208:211], v[4:7]
	v_mfma_f32_16x16x32_bf16 v[0:3], v[176:179], v[208:211], v[0:3]
	v_mfma_f32_16x16x32_bf16 v[52:55], v[172:175], v[188:191], v[52:55]
	v_mfma_f32_16x16x32_bf16 v[48:51], v[180:183], v[188:191], v[48:51]
	v_mfma_f32_16x16x32_bf16 v[36:39], v[172:175], v[196:199], v[36:39]
	v_mfma_f32_16x16x32_bf16 v[32:35], v[180:183], v[196:199], v[32:35]
	v_mfma_f32_16x16x32_bf16 v[20:23], v[172:175], v[204:207], v[20:23]
	v_mfma_f32_16x16x32_bf16 v[16:19], v[180:183], v[204:207], v[16:19]
	v_mfma_f32_16x16x32_bf16 v[4:7], v[172:175], v[212:215], v[4:7]
	v_mfma_f32_16x16x32_bf16 v[0:3], v[180:183], v[212:215], v[0:3]
	s_barrier
	s_cmp_ge_i32 s72, s57
	s_mov_b32 s28, s72
	s_cbranch_scc0 .LBB0_764
	s_mov_b32 s101, 1
	v_readlane_b32 s86, v255, 23
	v_readlane_b32 s87, v255, 24
	s_movk_i32 s76, 0x6000

.LBB0_899:
	s_add_i32 s33, s28, 2
	s_add_u32 s44, s42, 0x80
	s_addc_u32 s29, s43, 0
	s_add_i32 s46, 0, 0x10000
	s_cmp_eq_u32 s73, s28
	s_cselect_b32 s29, s71, s29
	s_cselect_b32 s28, s70, s44
	s_cselect_b32 s45, s27, s18
	s_cselect_b32 s44, s26, s7
	s_add_i32 s47, 0, 0x14000
	v_add_u32_e32 v40, s46, v181
	v_add_u32_e32 v170, s47, v181
	ds_read_b128 v[16:19], v40
	ds_read_b128 v[20:23], v40 offset:1024
	ds_read_b128 v[32:35], v40 offset:2048
	ds_read_b128 v[40:43], v40 offset:3072
	ds_read_b128 v[146:149], v170
	ds_read_b128 v[162:165], v170 offset:1024
	ds_read_b128 v[166:169], v170 offset:2048
	ds_read_b128 v[170:173], v170 offset:3072
	v_lshl_add_u64 v[214:215], s[42:43], 0, v[158:159]
	s_add_i32 m0, s86, 0xc000
	ds_read_b128 v[174:177], v184
	ds_read_b128 v[186:189], v184 offset:1024
	ds_read_b128 v[190:193], v184 offset:2048
	ds_read_b128 v[194:197], v184 offset:3072
	ds_read_b128 v[198:201], v184 offset:4096
	ds_read_b128 v[202:205], v184 offset:5120
	ds_read_b128 v[206:209], v184 offset:6144
	ds_read_b128 v[210:213], v184 offset:7168
	global_load_lds_dwordx4 v[214:215], off
	v_lshl_add_u64 v[214:215], s[42:43], 0, v[160:161]
	s_add_i32 m0, s86, 0xe000
	s_nop 0
	global_load_lds_dwordx4 v[214:215], off
	s_waitcnt vmcnt(8)
	s_waitcnt lgkmcnt(0)
	s_barrier
	s_waitcnt lgkmcnt(0)
	v_mfma_f32_16x16x32_bf16 v[138:141], v[16:19], v[174:177], v[138:141]
	v_mfma_f32_16x16x32_bf16 v[142:145], v[32:35], v[174:177], v[142:145]
	v_mfma_f32_16x16x32_bf16 v[124:127], v[16:19], v[190:193], v[124:127]
	v_mfma_f32_16x16x32_bf16 v[120:123], v[32:35], v[190:193], v[120:123]
	v_mfma_f32_16x16x32_bf16 v[108:111], v[16:19], v[198:201], v[108:111]
	v_mfma_f32_16x16x32_bf16 v[104:107], v[32:35], v[198:201], v[104:107]
	v_mfma_f32_16x16x32_bf16 v[92:95], v[16:19], v[206:209], v[92:95]
	v_mfma_f32_16x16x32_bf16 v[88:91], v[32:35], v[206:209], v[88:91]
	v_mfma_f32_16x16x32_bf16 v[138:141], v[20:23], v[186:189], v[138:141]
	v_mfma_f32_16x16x32_bf16 v[142:145], v[40:43], v[186:189], v[142:145]
	v_mfma_f32_16x16x32_bf16 v[124:127], v[20:23], v[194:197], v[124:127]
	v_mfma_f32_16x16x32_bf16 v[120:123], v[40:43], v[194:197], v[120:123]
	v_mfma_f32_16x16x32_bf16 v[108:111], v[20:23], v[202:205], v[108:111]
	v_mfma_f32_16x16x32_bf16 v[104:107], v[40:43], v[202:205], v[104:107]
	v_mfma_f32_16x16x32_bf16 v[92:95], v[20:23], v[210:213], v[92:95]
	v_mfma_f32_16x16x32_bf16 v[88:91], v[40:43], v[210:213], v[88:91]
	v_mfma_f32_16x16x32_bf16 v[134:137], v[146:149], v[174:177], v[134:137]
	v_mfma_f32_16x16x32_bf16 v[130:133], v[166:169], v[174:177], v[130:133]
	v_mfma_f32_16x16x32_bf16 v[116:119], v[146:149], v[190:193], v[116:119]
	v_mfma_f32_16x16x32_bf16 v[112:115], v[166:169], v[190:193], v[112:115]
	v_mfma_f32_16x16x32_bf16 v[100:103], v[146:149], v[198:201], v[100:103]
	v_mfma_f32_16x16x32_bf16 v[96:99], v[166:169], v[198:201], v[96:99]
	v_mfma_f32_16x16x32_bf16 v[84:87], v[146:149], v[206:209], v[84:87]
	v_mfma_f32_16x16x32_bf16 v[80:83], v[166:169], v[206:209], v[80:83]
	v_mfma_f32_16x16x32_bf16 v[134:137], v[162:165], v[186:189], v[134:137]
	v_mfma_f32_16x16x32_bf16 v[130:133], v[170:173], v[186:189], v[130:133]
	v_mfma_f32_16x16x32_bf16 v[116:119], v[162:165], v[194:197], v[116:119]
	v_mfma_f32_16x16x32_bf16 v[112:115], v[170:173], v[194:197], v[112:115]
	v_mfma_f32_16x16x32_bf16 v[100:103], v[162:165], v[202:205], v[100:103]
	v_mfma_f32_16x16x32_bf16 v[96:99], v[170:173], v[202:205], v[96:99]
	v_mfma_f32_16x16x32_bf16 v[84:87], v[162:165], v[210:213], v[84:87]
	v_mfma_f32_16x16x32_bf16 v[80:83], v[170:173], v[210:213], v[80:83]
	s_barrier
	s_add_i32 s46, s46, s67
	v_lshl_add_u64 v[214:215], s[44:45], 0, v[128:129]
	s_mov_b32 m0, s46
	ds_read_b128 v[174:177], v184 offset:16384
	ds_read_b128 v[186:189], v184 offset:17408
	ds_read_b128 v[190:193], v184 offset:18432
	ds_read_b128 v[194:197], v184 offset:19456
	ds_read_b128 v[198:201], v184 offset:20480
	ds_read_b128 v[202:205], v184 offset:21504
	ds_read_b128 v[206:209], v184 offset:22528
	ds_read_b128 v[210:213], v184 offset:23552
	global_load_lds_dwordx4 v[214:215], off
	s_add_i32 m0, s46, 0x2000
	v_lshl_add_u64 v[216:217], s[44:45], 0, v[154:155]
	s_add_u32 s44, s44, s2
	s_addc_u32 s45, s45, s3
	s_add_i32 s46, s47, s67
	global_load_lds_dwordx4 v[216:217], off
	v_lshl_add_u64 v[218:219], s[44:45], 0, v[128:129]
	s_mov_b32 m0, s46
	v_lshl_add_u64 v[220:221], s[44:45], 0, v[154:155]
	global_load_lds_dwordx4 v[218:219], off
	s_add_i32 m0, s46, 0x2000
	v_lshl_add_u64 v[222:223], s[28:29], 0, v[150:151]
	global_load_lds_dwordx4 v[220:221], off
	s_mov_b32 m0, s86
	v_lshl_add_u64 v[224:225], s[28:29], 0, v[152:153]
	global_load_lds_dwordx4 v[222:223], off
	s_mov_b32 m0, s87
	s_nop 0
	global_load_lds_dwordx4 v[224:225], off
	s_waitcnt vmcnt(8)
	s_waitcnt lgkmcnt(0)
	s_barrier
	s_waitcnt lgkmcnt(0)
	v_mfma_f32_16x16x32_bf16 v[76:79], v[16:19], v[174:177], v[76:79]
	v_mfma_f32_16x16x32_bf16 v[72:75], v[32:35], v[174:177], v[72:75]
	v_mfma_f32_16x16x32_bf16 v[60:63], v[16:19], v[190:193], v[60:63]
	v_mfma_f32_16x16x32_bf16 v[56:59], v[32:35], v[190:193], v[56:59]
	v_mfma_f32_16x16x32_bf16 v[44:47], v[16:19], v[198:201], v[44:47]
	v_mfma_f32_16x16x32_bf16 v[36:39], v[32:35], v[198:201], v[36:39]
	v_mfma_f32_16x16x32_bf16 v[12:15], v[16:19], v[206:209], v[12:15]
	v_mfma_f32_16x16x32_bf16 v[8:11], v[32:35], v[206:209], v[8:11]
	v_mfma_f32_16x16x32_bf16 v[76:79], v[20:23], v[186:189], v[76:79]
	v_mfma_f32_16x16x32_bf16 v[72:75], v[40:43], v[186:189], v[72:75]
	v_mfma_f32_16x16x32_bf16 v[60:63], v[20:23], v[194:197], v[60:63]
	v_mfma_f32_16x16x32_bf16 v[56:59], v[40:43], v[194:197], v[56:59]
	v_mfma_f32_16x16x32_bf16 v[44:47], v[20:23], v[202:205], v[44:47]
	v_mfma_f32_16x16x32_bf16 v[36:39], v[40:43], v[202:205], v[36:39]
	v_mfma_f32_16x16x32_bf16 v[12:15], v[20:23], v[210:213], v[12:15]
	v_mfma_f32_16x16x32_bf16 v[8:11], v[40:43], v[210:213], v[8:11]
	v_mfma_f32_16x16x32_bf16 v[28:31], v[146:149], v[198:201], v[28:31]
	v_mfma_f32_16x16x32_bf16 v[24:27], v[166:169], v[198:201], v[24:27]
	v_mfma_f32_16x16x32_bf16 v[4:7], v[146:149], v[206:209], v[4:7]
	v_mfma_f32_16x16x32_bf16 v[0:3], v[166:169], v[206:209], v[0:3]
	v_mfma_f32_16x16x32_bf16 v[16:19], v[146:149], v[174:177], v[68:71]
	v_mfma_f32_16x16x32_bf16 v[20:23], v[166:169], v[174:177], v[64:67]
	v_mfma_f32_16x16x32_bf16 v[32:35], v[146:149], v[190:193], v[52:55]
	v_mfma_f32_16x16x32_bf16 v[40:43], v[166:169], v[190:193], v[48:51]
	v_mfma_f32_16x16x32_bf16 v[28:31], v[162:165], v[202:205], v[28:31]
	v_mfma_f32_16x16x32_bf16 v[24:27], v[170:173], v[202:205], v[24:27]
	v_mfma_f32_16x16x32_bf16 v[4:7], v[162:165], v[210:213], v[4:7]
	v_mfma_f32_16x16x32_bf16 v[0:3], v[170:173], v[210:213], v[0:3]
	v_mfma_f32_16x16x32_bf16 v[16:19], v[162:165], v[186:189], v[16:19]
	v_mfma_f32_16x16x32_bf16 v[20:23], v[170:173], v[186:189], v[20:23]
	v_mfma_f32_16x16x32_bf16 v[32:35], v[162:165], v[194:197], v[32:35]
	v_mfma_f32_16x16x32_bf16 v[40:43], v[170:173], v[194:197], v[40:43]
	s_barrier
	s_add_i32 s44, 0, 0x18000
	s_add_i32 s45, 0, 0x1c000
	v_add_u32_e32 v68, s44, v181
	v_add_u32_e32 v170, s45, v181
	ds_read_b128 v[48:51], v68
	ds_read_b128 v[52:55], v68 offset:1024
	ds_read_b128 v[64:67], v68 offset:2048
	ds_read_b128 v[68:71], v68 offset:3072
	ds_read_b128 v[146:149], v170
	ds_read_b128 v[162:165], v170 offset:1024
	ds_read_b128 v[166:169], v170 offset:2048
	ds_read_b128 v[170:173], v170 offset:3072
	s_add_u32 s28, s28, s2
	s_addc_u32 s29, s29, s3
	s_mov_b32 m0, s24
	v_lshl_add_u64 v[226:227], s[28:29], 0, v[150:151]
	ds_read_b128 v[174:177], v184 offset:32768
	ds_read_b128 v[186:189], v184 offset:33792
	ds_read_b128 v[190:193], v184 offset:34816
	ds_read_b128 v[194:197], v184 offset:35840
	ds_read_b128 v[198:201], v184 offset:36864
	ds_read_b128 v[202:205], v184 offset:37888
	ds_read_b128 v[206:209], v184 offset:38912
	ds_read_b128 v[210:213], v184 offset:39936
	global_load_lds_dwordx4 v[226:227], off
	v_lshl_add_u64 v[226:227], s[28:29], 0, v[152:153]
	s_mov_b32 m0, s25
	s_nop 0
	global_load_lds_dwordx4 v[226:227], off
	s_waitcnt vmcnt(8)
	s_waitcnt lgkmcnt(0)
	s_barrier
	s_waitcnt lgkmcnt(0)
	v_mfma_f32_16x16x32_bf16 v[138:141], v[48:51], v[174:177], v[138:141]
	v_mfma_f32_16x16x32_bf16 v[142:145], v[64:67], v[174:177], v[142:145]
	v_mfma_f32_16x16x32_bf16 v[124:127], v[48:51], v[190:193], v[124:127]
	v_mfma_f32_16x16x32_bf16 v[120:123], v[64:67], v[190:193], v[120:123]
	v_mfma_f32_16x16x32_bf16 v[108:111], v[48:51], v[198:201], v[108:111]
	v_mfma_f32_16x16x32_bf16 v[104:107], v[64:67], v[198:201], v[104:107]
	v_mfma_f32_16x16x32_bf16 v[92:95], v[48:51], v[206:209], v[92:95]
	v_mfma_f32_16x16x32_bf16 v[88:91], v[64:67], v[206:209], v[88:91]
	v_mfma_f32_16x16x32_bf16 v[138:141], v[52:55], v[186:189], v[138:141]
	v_mfma_f32_16x16x32_bf16 v[142:145], v[68:71], v[186:189], v[142:145]
	v_mfma_f32_16x16x32_bf16 v[124:127], v[52:55], v[194:197], v[124:127]
	v_mfma_f32_16x16x32_bf16 v[120:123], v[68:71], v[194:197], v[120:123]
	v_mfma_f32_16x16x32_bf16 v[108:111], v[52:55], v[202:205], v[108:111]
	v_mfma_f32_16x16x32_bf16 v[104:107], v[68:71], v[202:205], v[104:107]
	v_mfma_f32_16x16x32_bf16 v[92:95], v[52:55], v[210:213], v[92:95]
	v_mfma_f32_16x16x32_bf16 v[88:91], v[68:71], v[210:213], v[88:91]
	v_mfma_f32_16x16x32_bf16 v[134:137], v[146:149], v[174:177], v[134:137]
	v_mfma_f32_16x16x32_bf16 v[130:133], v[166:169], v[174:177], v[130:133]
	v_mfma_f32_16x16x32_bf16 v[116:119], v[146:149], v[190:193], v[116:119]
	v_mfma_f32_16x16x32_bf16 v[112:115], v[166:169], v[190:193], v[112:115]
	v_mfma_f32_16x16x32_bf16 v[100:103], v[146:149], v[198:201], v[100:103]
	v_mfma_f32_16x16x32_bf16 v[96:99], v[166:169], v[198:201], v[96:99]
	v_mfma_f32_16x16x32_bf16 v[84:87], v[146:149], v[206:209], v[84:87]
	v_mfma_f32_16x16x32_bf16 v[80:83], v[166:169], v[206:209], v[80:83]
	v_mfma_f32_16x16x32_bf16 v[134:137], v[162:165], v[186:189], v[134:137]
	v_mfma_f32_16x16x32_bf16 v[130:133], v[170:173], v[186:189], v[130:133]
	v_mfma_f32_16x16x32_bf16 v[116:119], v[162:165], v[194:197], v[116:119]
	v_mfma_f32_16x16x32_bf16 v[112:115], v[170:173], v[194:197], v[112:115]
	v_mfma_f32_16x16x32_bf16 v[100:103], v[162:165], v[202:205], v[100:103]
	v_mfma_f32_16x16x32_bf16 v[96:99], v[170:173], v[202:205], v[96:99]
	v_mfma_f32_16x16x32_bf16 v[84:87], v[162:165], v[210:213], v[84:87]
	v_mfma_f32_16x16x32_bf16 v[80:83], v[170:173], v[210:213], v[80:83]
	s_barrier
	s_add_i32 s28, s44, s67
	v_lshl_add_u64 v[214:215], v[214:215], 0, s[34:35]
	s_mov_b32 m0, s28
	ds_read_b128 v[174:177], v184 offset:49152
	ds_read_b128 v[186:189], v184 offset:50176
	ds_read_b128 v[190:193], v184 offset:51200
	ds_read_b128 v[194:197], v184 offset:52224
	ds_read_b128 v[198:201], v184 offset:53248
	ds_read_b128 v[202:205], v184 offset:54272
	ds_read_b128 v[206:209], v184 offset:55296
	ds_read_b128 v[210:213], v184 offset:56320
	global_load_lds_dwordx4 v[214:215], off
	v_lshl_add_u64 v[214:215], v[216:217], 0, s[34:35]
	s_add_i32 m0, s28, 0x2000
	s_add_i32 s28, s45, s67
	global_load_lds_dwordx4 v[214:215], off
	v_lshl_add_u64 v[214:215], v[218:219], 0, s[34:35]
	s_mov_b32 m0, s28
	s_nop 0
	global_load_lds_dwordx4 v[214:215], off
	v_lshl_add_u64 v[214:215], v[220:221], 0, s[34:35]
	s_add_i32 m0, s28, 0x2000
	s_nop 0
	global_load_lds_dwordx4 v[214:215], off
	v_lshl_add_u64 v[214:215], v[222:223], 0, s[34:35]
	s_mov_b32 m0, s88
	s_nop 0
	global_load_lds_dwordx4 v[214:215], off
	v_lshl_add_u64 v[214:215], v[224:225], 0, s[34:35]
	s_mov_b32 m0, s89
	s_nop 0
	global_load_lds_dwordx4 v[214:215], off
	s_add_u32 s42, s42, 0x100
	s_addc_u32 s43, s43, 0
	s_add_u32 s7, s7, 0x100
	s_addc_u32 s18, s18, 0
	s_waitcnt vmcnt(8)
	s_waitcnt lgkmcnt(0)
	s_barrier
	s_waitcnt lgkmcnt(0)
	v_mfma_f32_16x16x32_bf16 v[76:79], v[48:51], v[174:177], v[76:79]
	v_mfma_f32_16x16x32_bf16 v[72:75], v[64:67], v[174:177], v[72:75]
	v_mfma_f32_16x16x32_bf16 v[60:63], v[48:51], v[190:193], v[60:63]
	v_mfma_f32_16x16x32_bf16 v[56:59], v[64:67], v[190:193], v[56:59]
	v_mfma_f32_16x16x32_bf16 v[44:47], v[48:51], v[198:201], v[44:47]
	v_mfma_f32_16x16x32_bf16 v[36:39], v[64:67], v[198:201], v[36:39]
	v_mfma_f32_16x16x32_bf16 v[12:15], v[48:51], v[206:209], v[12:15]
	v_mfma_f32_16x16x32_bf16 v[8:11], v[64:67], v[206:209], v[8:11]
	v_mfma_f32_16x16x32_bf16 v[76:79], v[52:55], v[186:189], v[76:79]
	v_mfma_f32_16x16x32_bf16 v[72:75], v[68:71], v[186:189], v[72:75]
	v_mfma_f32_16x16x32_bf16 v[60:63], v[52:55], v[194:197], v[60:63]
	v_mfma_f32_16x16x32_bf16 v[56:59], v[68:71], v[194:197], v[56:59]
	v_mfma_f32_16x16x32_bf16 v[44:47], v[52:55], v[202:205], v[44:47]
	v_mfma_f32_16x16x32_bf16 v[36:39], v[68:71], v[202:205], v[36:39]
	v_mfma_f32_16x16x32_bf16 v[12:15], v[52:55], v[210:213], v[12:15]
	v_mfma_f32_16x16x32_bf16 v[8:11], v[68:71], v[210:213], v[8:11]
	v_mfma_f32_16x16x32_bf16 v[16:19], v[146:149], v[174:177], v[16:19]
	v_mfma_f32_16x16x32_bf16 v[68:71], v[162:165], v[186:189], v[16:19]
	v_mfma_f32_16x16x32_bf16 v[16:19], v[166:169], v[174:177], v[20:23]
	v_mfma_f32_16x16x32_bf16 v[64:67], v[170:173], v[186:189], v[16:19]
	v_mfma_f32_16x16x32_bf16 v[16:19], v[146:149], v[190:193], v[32:35]
	v_mfma_f32_16x16x32_bf16 v[52:55], v[162:165], v[194:197], v[16:19]
	v_mfma_f32_16x16x32_bf16 v[16:19], v[166:169], v[190:193], v[40:43]
	v_mfma_f32_16x16x32_bf16 v[48:51], v[170:173], v[194:197], v[16:19]
	v_mfma_f32_16x16x32_bf16 v[16:19], v[146:149], v[198:201], v[28:31]
	v_mfma_f32_16x16x32_bf16 v[28:31], v[162:165], v[202:205], v[16:19]
	v_mfma_f32_16x16x32_bf16 v[16:19], v[166:169], v[198:201], v[24:27]
	v_mfma_f32_16x16x32_bf16 v[4:7], v[146:149], v[206:209], v[4:7]
	v_mfma_f32_16x16x32_bf16 v[0:3], v[166:169], v[206:209], v[0:3]
	v_mfma_f32_16x16x32_bf16 v[24:27], v[170:173], v[202:205], v[16:19]
	v_mfma_f32_16x16x32_bf16 v[4:7], v[162:165], v[210:213], v[4:7]
	v_mfma_f32_16x16x32_bf16 v[0:3], v[170:173], v[210:213], v[0:3]
	s_barrier
	s_cmp_ge_i32 s33, s90
	s_mov_b32 s28, s33
	s_cbranch_scc0 .LBB0_899

.Lrx_join_1165_1:
	s_mov_b32 s101, 0
	s_waitcnt lgkmcnt(0)
	s_barrier
	s_waitcnt lgkmcnt(0)
	v_mfma_f32_16x16x32_bf16 v[120:123], v[40:43], v[146:149], v[120:123]
	v_mfma_f32_16x16x32_bf16 v[28:31], v[64:67], v[146:149], v[28:31]
	v_mfma_f32_16x16x32_bf16 v[108:111], v[40:43], v[158:161], v[108:111]
	v_mfma_f32_16x16x32_bf16 v[20:23], v[64:67], v[158:161], v[20:23]
	v_mfma_f32_16x16x32_bf16 v[96:99], v[40:43], v[190:193], v[96:99]
	v_mfma_f32_16x16x32_bf16 v[12:15], v[64:67], v[190:193], v[12:15]
	v_mfma_f32_16x16x32_bf16 v[4:7], v[64:67], v[206:209], v[4:7]
	v_mfma_f32_16x16x32_bf16 v[120:123], v[52:55], v[150:153], v[120:123]
	v_mfma_f32_16x16x32_bf16 v[28:31], v[76:79], v[150:153], v[28:31]
	v_mfma_f32_16x16x32_bf16 v[108:111], v[52:55], v[186:189], v[108:111]
	v_mfma_f32_16x16x32_bf16 v[20:23], v[76:79], v[186:189], v[20:23]
	v_mfma_f32_16x16x32_bf16 v[96:99], v[52:55], v[198:201], v[96:99]
	v_mfma_f32_16x16x32_bf16 v[12:15], v[76:79], v[198:201], v[12:15]
	v_mfma_f32_16x16x32_bf16 v[40:43], v[40:43], v[206:209], v[84:87]
	v_mfma_f32_16x16x32_bf16 v[4:7], v[76:79], v[210:213], v[4:7]
	v_mfma_f32_16x16x32_bf16 v[40:43], v[52:55], v[210:213], v[40:43]
	v_mfma_f32_16x16x32_bf16 v[24:27], v[112:115], v[146:149], v[24:27]
	v_mfma_f32_16x16x32_bf16 v[16:19], v[112:115], v[158:161], v[16:19]
	v_mfma_f32_16x16x32_bf16 v[8:11], v[112:115], v[190:193], v[8:11]
	v_mfma_f32_16x16x32_bf16 v[80:83], v[88:91], v[206:209], v[80:83]
	v_mfma_f32_16x16x32_bf16 v[0:3], v[112:115], v[206:209], v[0:3]
	v_mfma_f32_16x16x32_bf16 v[52:55], v[88:91], v[146:149], v[116:119]
	v_mfma_f32_16x16x32_bf16 v[24:27], v[124:127], v[150:153], v[24:27]
	v_mfma_f32_16x16x32_bf16 v[64:67], v[88:91], v[158:161], v[104:107]
	v_mfma_f32_16x16x32_bf16 v[16:19], v[124:127], v[186:189], v[16:19]
	v_mfma_f32_16x16x32_bf16 v[76:79], v[88:91], v[190:193], v[92:95]
	v_mfma_f32_16x16x32_bf16 v[8:11], v[124:127], v[198:201], v[8:11]
	v_mfma_f32_16x16x32_bf16 v[80:83], v[100:103], v[210:213], v[80:83]
	v_mfma_f32_16x16x32_bf16 v[0:3], v[124:127], v[210:213], v[0:3]
	v_mfma_f32_16x16x32_bf16 v[52:55], v[100:103], v[150:153], v[52:55]
	v_mfma_f32_16x16x32_bf16 v[64:67], v[100:103], v[186:189], v[64:67]
	v_mfma_f32_16x16x32_bf16 v[76:79], v[100:103], v[198:201], v[76:79]
	s_barrier
	s_add_i32 s53, 0, 0x18000
	s_add_i32 s76, 0, 0x1c000
	v_add_u32_e32 v100, s53, v203
	v_add_u32_e32 v104, s76, v203
	ds_read_b128 v[84:87], v100
	ds_read_b128 v[88:91], v100 offset:1024
	ds_read_b128 v[92:95], v100 offset:2048
	ds_read_b128 v[100:103], v100 offset:3072
	ds_read_b128 v[112:115], v104
	ds_read_b128 v[124:127], v104 offset:1024
	ds_read_b128 v[146:149], v104 offset:2048
	ds_read_b128 v[150:153], v104 offset:3072
	s_add_u32 s28, s28, s36
	s_addc_u32 s29, s29, s37
	s_mov_b32 m0, s64
	v_lshl_add_u64 v[158:159], s[28:29], 0, v[174:175]
	ds_read_b128 v[104:107], v205 offset:32768
	ds_read_b128 v[116:119], v205 offset:33792
	ds_read_b128 v[186:189], v205 offset:34816
	ds_read_b128 v[190:193], v205 offset:35840
	ds_read_b128 v[198:201], v205 offset:36864
	ds_read_b128 v[206:209], v205 offset:37888
	ds_read_b128 v[210:213], v205 offset:38912
	ds_read_b128 v[214:217], v205 offset:39936
	global_load_lds_dwordx4 v[158:159], off
	v_lshl_add_u64 v[158:159], s[28:29], 0, v[178:179]
	s_mov_b32 m0, s65
	s_nop 0
	global_load_lds_dwordx4 v[158:159], off
	s_waitcnt vmcnt(8)
	s_waitcnt lgkmcnt(0)
	s_barrier
	s_waitcnt lgkmcnt(0)
	v_mfma_f32_16x16x32_bf16 v[158:161], v[84:87], v[104:107], v[170:173]
	v_mfma_f32_16x16x32_bf16 v[170:173], v[88:91], v[116:119], v[158:161]
	v_mfma_f32_16x16x32_bf16 v[72:75], v[92:95], v[104:107], v[72:75]
	v_mfma_f32_16x16x32_bf16 v[158:161], v[84:87], v[186:189], v[162:165]
	v_mfma_f32_16x16x32_bf16 v[60:63], v[92:95], v[186:189], v[60:63]
	v_mfma_f32_16x16x32_bf16 v[154:157], v[84:87], v[198:201], v[154:157]
	v_mfma_f32_16x16x32_bf16 v[48:51], v[92:95], v[198:201], v[48:51]
	v_mfma_f32_16x16x32_bf16 v[134:137], v[84:87], v[210:213], v[134:137]
	v_mfma_f32_16x16x32_bf16 v[36:39], v[92:95], v[210:213], v[36:39]
	v_mfma_f32_16x16x32_bf16 v[72:75], v[100:103], v[116:119], v[72:75]
	v_mfma_f32_16x16x32_bf16 v[162:165], v[88:91], v[190:193], v[158:161]
	v_mfma_f32_16x16x32_bf16 v[60:63], v[100:103], v[190:193], v[60:63]
	v_mfma_f32_16x16x32_bf16 v[154:157], v[88:91], v[206:209], v[154:157]
	v_mfma_f32_16x16x32_bf16 v[48:51], v[100:103], v[206:209], v[48:51]
	v_mfma_f32_16x16x32_bf16 v[134:137], v[88:91], v[214:217], v[134:137]
	v_mfma_f32_16x16x32_bf16 v[36:39], v[100:103], v[214:217], v[36:39]
	v_mfma_f32_16x16x32_bf16 v[158:161], v[112:115], v[104:107], v[166:169]
	v_mfma_f32_16x16x32_bf16 v[68:71], v[146:149], v[104:107], v[68:71]
	v_mfma_f32_16x16x32_bf16 v[104:107], v[112:115], v[186:189], v[138:141]
	v_mfma_f32_16x16x32_bf16 v[166:169], v[124:127], v[116:119], v[158:161]
	v_mfma_f32_16x16x32_bf16 v[158:161], v[124:127], v[190:193], v[104:107]
	v_mfma_f32_16x16x32_bf16 v[104:107], v[112:115], v[198:201], v[142:145]
	v_mfma_f32_16x16x32_bf16 v[56:59], v[146:149], v[186:189], v[56:59]
	v_mfma_f32_16x16x32_bf16 v[142:145], v[124:127], v[206:209], v[104:107]
	v_mfma_f32_16x16x32_bf16 v[44:47], v[146:149], v[198:201], v[44:47]
	v_mfma_f32_16x16x32_bf16 v[104:107], v[112:115], v[210:213], v[130:133]
	v_mfma_f32_16x16x32_bf16 v[32:35], v[146:149], v[210:213], v[32:35]
	v_mfma_f32_16x16x32_bf16 v[68:71], v[150:153], v[116:119], v[68:71]
	v_mfma_f32_16x16x32_bf16 v[56:59], v[150:153], v[190:193], v[56:59]
	v_mfma_f32_16x16x32_bf16 v[44:47], v[150:153], v[206:209], v[44:47]
	v_mfma_f32_16x16x32_bf16 v[130:133], v[124:127], v[214:217], v[104:107]
	v_mfma_f32_16x16x32_bf16 v[32:35], v[150:153], v[214:217], v[32:35]
	s_barrier
	s_add_i32 s28, s53, s61
	v_lshl_add_u64 v[116:117], v[218:219], 0, s[34:35]
	s_mov_b32 m0, s28
	ds_read_b128 v[104:107], v205 offset:49152
	ds_read_b128 v[138:141], v205 offset:50176
	ds_read_b128 v[186:189], v205 offset:51200
	ds_read_b128 v[190:193], v205 offset:52224
	ds_read_b128 v[198:201], v205 offset:53248
	ds_read_b128 v[206:209], v205 offset:54272
	ds_read_b128 v[210:213], v205 offset:55296
	ds_read_b128 v[214:217], v205 offset:56320
	global_load_lds_dwordx4 v[116:117], off
	v_lshl_add_u64 v[116:117], v[220:221], 0, s[34:35]
	s_add_i32 m0, s28, 0x2000
	s_add_i32 s28, s76, s61
	global_load_lds_dwordx4 v[116:117], off
	v_lshl_add_u64 v[116:117], v[222:223], 0, s[34:35]
	s_mov_b32 m0, s28
	s_nop 0
	global_load_lds_dwordx4 v[116:117], off
	v_lshl_add_u64 v[116:117], v[224:225], 0, s[34:35]
	s_add_i32 m0, s28, 0x2000
	s_nop 0
	global_load_lds_dwordx4 v[116:117], off
	v_lshl_add_u64 v[116:117], v[226:227], 0, s[34:35]
	s_mov_b32 m0, s67
	s_nop 0
	global_load_lds_dwordx4 v[116:117], off
	v_lshl_add_u64 v[116:117], v[228:229], 0, s[34:35]
	s_mov_b32 m0, s48
	s_nop 0
	global_load_lds_dwordx4 v[116:117], off
	s_add_u32 s58, s58, 0x100
	s_addc_u32 s59, s59, 0
	s_add_u32 s18, s18, 0x100
	s_addc_u32 s33, s33, 0
	s_waitcnt vmcnt(8)
	s_waitcnt lgkmcnt(0)
	s_barrier
	s_waitcnt lgkmcnt(0)
	v_mfma_f32_16x16x32_bf16 v[116:119], v[84:87], v[104:107], v[120:123]
	v_mfma_f32_16x16x32_bf16 v[28:31], v[92:95], v[104:107], v[28:31]
	v_mfma_f32_16x16x32_bf16 v[108:111], v[84:87], v[186:189], v[108:111]
	v_mfma_f32_16x16x32_bf16 v[20:23], v[92:95], v[186:189], v[20:23]
	v_mfma_f32_16x16x32_bf16 v[96:99], v[84:87], v[198:201], v[96:99]
	v_mfma_f32_16x16x32_bf16 v[12:15], v[92:95], v[198:201], v[12:15]
	v_mfma_f32_16x16x32_bf16 v[40:43], v[84:87], v[210:213], v[40:43]
	v_mfma_f32_16x16x32_bf16 v[4:7], v[92:95], v[210:213], v[4:7]
	v_mfma_f32_16x16x32_bf16 v[120:123], v[88:91], v[138:141], v[116:119]
	v_mfma_f32_16x16x32_bf16 v[28:31], v[100:103], v[138:141], v[28:31]
	v_mfma_f32_16x16x32_bf16 v[108:111], v[88:91], v[190:193], v[108:111]
	v_mfma_f32_16x16x32_bf16 v[20:23], v[100:103], v[190:193], v[20:23]
	v_mfma_f32_16x16x32_bf16 v[96:99], v[88:91], v[206:209], v[96:99]
	v_mfma_f32_16x16x32_bf16 v[12:15], v[100:103], v[206:209], v[12:15]
	v_mfma_f32_16x16x32_bf16 v[84:87], v[88:91], v[214:217], v[40:43]
	v_mfma_f32_16x16x32_bf16 v[4:7], v[100:103], v[214:217], v[4:7]
	v_mfma_f32_16x16x32_bf16 v[40:43], v[112:115], v[104:107], v[52:55]
	v_mfma_f32_16x16x32_bf16 v[116:119], v[124:127], v[138:141], v[40:43]
	v_mfma_f32_16x16x32_bf16 v[40:43], v[112:115], v[186:189], v[64:67]
	v_mfma_f32_16x16x32_bf16 v[24:27], v[146:149], v[104:107], v[24:27]
	v_mfma_f32_16x16x32_bf16 v[104:107], v[124:127], v[190:193], v[40:43]
	v_mfma_f32_16x16x32_bf16 v[40:43], v[112:115], v[198:201], v[76:79]
	v_mfma_f32_16x16x32_bf16 v[16:19], v[146:149], v[186:189], v[16:19]
	v_mfma_f32_16x16x32_bf16 v[92:95], v[124:127], v[206:209], v[40:43]
	v_mfma_f32_16x16x32_bf16 v[8:11], v[146:149], v[198:201], v[8:11]
	v_mfma_f32_16x16x32_bf16 v[40:43], v[112:115], v[210:213], v[80:83]
	v_mfma_f32_16x16x32_bf16 v[0:3], v[146:149], v[210:213], v[0:3]
	v_mfma_f32_16x16x32_bf16 v[24:27], v[150:153], v[138:141], v[24:27]
	v_mfma_f32_16x16x32_bf16 v[16:19], v[150:153], v[190:193], v[16:19]
	v_mfma_f32_16x16x32_bf16 v[8:11], v[150:153], v[206:209], v[8:11]
	v_mfma_f32_16x16x32_bf16 v[80:83], v[124:127], v[214:217], v[40:43]
	v_mfma_f32_16x16x32_bf16 v[0:3], v[150:153], v[214:217], v[0:3]
	s_barrier
	s_cmp_ge_i32 s52, s49
	s_mov_b32 s28, s52
	s_cbranch_scc0 .LBB0_1165
	s_mov_b32 s101, 1
	v_readlane_b32 s86, v255, 23
	v_readlane_b32 s87, v255, 24
	s_movk_i32 s76, 0x6000

.Lrx_join_1646_1:
	s_mov_b32 s101, 0
	s_waitcnt lgkmcnt(0)
	s_barrier
	s_waitcnt lgkmcnt(0)
	v_mfma_f32_16x16x32_bf16 v[60:63], v[152:155], v[184:187], v[60:63]
	v_mfma_f32_16x16x32_bf16 v[56:59], v[160:163], v[184:187], v[56:59]
	v_mfma_f32_16x16x32_bf16 v[44:47], v[152:155], v[192:195], v[44:47]
	v_mfma_f32_16x16x32_bf16 v[40:43], v[160:163], v[192:195], v[40:43]
	v_mfma_f32_16x16x32_bf16 v[28:31], v[152:155], v[200:203], v[28:31]
	v_mfma_f32_16x16x32_bf16 v[24:27], v[160:163], v[200:203], v[24:27]
	v_mfma_f32_16x16x32_bf16 v[12:15], v[152:155], v[208:211], v[12:15]
	v_mfma_f32_16x16x32_bf16 v[8:11], v[160:163], v[208:211], v[8:11]
	v_mfma_f32_16x16x32_bf16 v[60:63], v[156:159], v[188:191], v[60:63]
	v_mfma_f32_16x16x32_bf16 v[56:59], v[164:167], v[188:191], v[56:59]
	v_mfma_f32_16x16x32_bf16 v[44:47], v[156:159], v[196:199], v[44:47]
	v_mfma_f32_16x16x32_bf16 v[40:43], v[164:167], v[196:199], v[40:43]
	v_mfma_f32_16x16x32_bf16 v[28:31], v[156:159], v[204:207], v[28:31]
	v_mfma_f32_16x16x32_bf16 v[24:27], v[164:167], v[204:207], v[24:27]
	v_mfma_f32_16x16x32_bf16 v[12:15], v[156:159], v[212:215], v[12:15]
	v_mfma_f32_16x16x32_bf16 v[8:11], v[164:167], v[212:215], v[8:11]
	v_mfma_f32_16x16x32_bf16 v[52:55], v[168:171], v[184:187], v[52:55]
	v_mfma_f32_16x16x32_bf16 v[48:51], v[176:179], v[184:187], v[48:51]
	v_mfma_f32_16x16x32_bf16 v[36:39], v[168:171], v[192:195], v[36:39]
	v_mfma_f32_16x16x32_bf16 v[32:35], v[176:179], v[192:195], v[32:35]
	v_mfma_f32_16x16x32_bf16 v[20:23], v[168:171], v[200:203], v[20:23]
	v_mfma_f32_16x16x32_bf16 v[16:19], v[176:179], v[200:203], v[16:19]
	v_mfma_f32_16x16x32_bf16 v[4:7], v[168:171], v[208:211], v[4:7]
	v_mfma_f32_16x16x32_bf16 v[0:3], v[176:179], v[208:211], v[0:3]
	v_mfma_f32_16x16x32_bf16 v[52:55], v[172:175], v[188:191], v[52:55]
	v_mfma_f32_16x16x32_bf16 v[48:51], v[180:183], v[188:191], v[48:51]
	v_mfma_f32_16x16x32_bf16 v[36:39], v[172:175], v[196:199], v[36:39]
	v_mfma_f32_16x16x32_bf16 v[32:35], v[180:183], v[196:199], v[32:35]
	v_mfma_f32_16x16x32_bf16 v[20:23], v[172:175], v[204:207], v[20:23]
	v_mfma_f32_16x16x32_bf16 v[16:19], v[180:183], v[204:207], v[16:19]
	v_mfma_f32_16x16x32_bf16 v[4:7], v[172:175], v[212:215], v[4:7]
	v_mfma_f32_16x16x32_bf16 v[0:3], v[180:183], v[212:215], v[0:3]
	s_barrier
	s_add_i32 s71, 0, 0x18000
	v_add_u32_e32 v128, s71, v149
	s_add_i32 s72, 0, 0x1c000
	ds_read_b128 v[152:155], v128
	ds_read_b128 v[156:159], v128 offset:1024
	ds_read_b128 v[160:163], v128 offset:2048
	ds_read_b128 v[164:167], v128 offset:3072
	v_add_u32_e32 v128, s72, v149
	ds_read_b128 v[168:171], v128
	ds_read_b128 v[172:175], v128 offset:1024
	ds_read_b128 v[176:179], v128 offset:2048
	ds_read_b128 v[180:183], v128 offset:3072
	s_add_u32 s28, s28, s14
	s_addc_u32 s29, s29, s15
	s_mov_b32 m0, s49
	v_lshl_add_u64 v[226:227], s[28:29], 0, v[130:131]
	ds_read_b128 v[184:187], v151 offset:32768
	ds_read_b128 v[188:191], v151 offset:33792
	ds_read_b128 v[192:195], v151 offset:34816
	ds_read_b128 v[196:199], v151 offset:35840
	ds_read_b128 v[200:203], v151 offset:36864
	ds_read_b128 v[204:207], v151 offset:37888
	ds_read_b128 v[208:211], v151 offset:38912
	ds_read_b128 v[212:215], v151 offset:39936
	global_load_lds_dwordx4 v[226:227], off
	v_lshl_add_u64 v[226:227], s[28:29], 0, v[134:135]
	s_mov_b32 m0, s50
	s_nop 0
	global_load_lds_dwordx4 v[226:227], off
	s_waitcnt vmcnt(8)
	s_waitcnt lgkmcnt(0)
	s_barrier
	s_waitcnt lgkmcnt(0)
	v_mfma_f32_16x16x32_bf16 v[120:123], v[152:155], v[184:187], v[120:123]
	v_mfma_f32_16x16x32_bf16 v[124:127], v[160:163], v[184:187], v[124:127]
	v_mfma_f32_16x16x32_bf16 v[108:111], v[152:155], v[192:195], v[108:111]
	v_mfma_f32_16x16x32_bf16 v[104:107], v[160:163], v[192:195], v[104:107]
	v_mfma_f32_16x16x32_bf16 v[92:95], v[152:155], v[200:203], v[92:95]
	v_mfma_f32_16x16x32_bf16 v[88:91], v[160:163], v[200:203], v[88:91]
	v_mfma_f32_16x16x32_bf16 v[76:79], v[152:155], v[208:211], v[76:79]
	v_mfma_f32_16x16x32_bf16 v[72:75], v[160:163], v[208:211], v[72:75]
	v_mfma_f32_16x16x32_bf16 v[120:123], v[156:159], v[188:191], v[120:123]
	v_mfma_f32_16x16x32_bf16 v[124:127], v[164:167], v[188:191], v[124:127]
	v_mfma_f32_16x16x32_bf16 v[108:111], v[156:159], v[196:199], v[108:111]
	v_mfma_f32_16x16x32_bf16 v[104:107], v[164:167], v[196:199], v[104:107]
	v_mfma_f32_16x16x32_bf16 v[92:95], v[156:159], v[204:207], v[92:95]
	v_mfma_f32_16x16x32_bf16 v[88:91], v[164:167], v[204:207], v[88:91]
	v_mfma_f32_16x16x32_bf16 v[76:79], v[156:159], v[212:215], v[76:79]
	v_mfma_f32_16x16x32_bf16 v[72:75], v[164:167], v[212:215], v[72:75]
	v_mfma_f32_16x16x32_bf16 v[116:119], v[168:171], v[184:187], v[116:119]
	v_mfma_f32_16x16x32_bf16 v[112:115], v[176:179], v[184:187], v[112:115]
	v_mfma_f32_16x16x32_bf16 v[100:103], v[168:171], v[192:195], v[100:103]
	v_mfma_f32_16x16x32_bf16 v[96:99], v[176:179], v[192:195], v[96:99]
	v_mfma_f32_16x16x32_bf16 v[84:87], v[168:171], v[200:203], v[84:87]
	v_mfma_f32_16x16x32_bf16 v[80:83], v[176:179], v[200:203], v[80:83]
	v_mfma_f32_16x16x32_bf16 v[68:71], v[168:171], v[208:211], v[68:71]
	v_mfma_f32_16x16x32_bf16 v[64:67], v[176:179], v[208:211], v[64:67]
	v_mfma_f32_16x16x32_bf16 v[116:119], v[172:175], v[188:191], v[116:119]
	v_mfma_f32_16x16x32_bf16 v[112:115], v[180:183], v[188:191], v[112:115]
	v_mfma_f32_16x16x32_bf16 v[100:103], v[172:175], v[196:199], v[100:103]
	v_mfma_f32_16x16x32_bf16 v[96:99], v[180:183], v[196:199], v[96:99]
	v_mfma_f32_16x16x32_bf16 v[84:87], v[172:175], v[204:207], v[84:87]
	v_mfma_f32_16x16x32_bf16 v[80:83], v[180:183], v[204:207], v[80:83]
	v_mfma_f32_16x16x32_bf16 v[68:71], v[172:175], v[212:215], v[68:71]
	v_mfma_f32_16x16x32_bf16 v[64:67], v[180:183], v[212:215], v[64:67]
	s_barrier
	s_add_i32 s28, s71, s18
	v_lshl_add_u64 v[142:143], v[142:143], 0, s[34:35]
	s_mov_b32 m0, s28
	ds_read_b128 v[184:187], v151 offset:49152
	ds_read_b128 v[188:191], v151 offset:50176
	ds_read_b128 v[192:195], v151 offset:51200
	ds_read_b128 v[196:199], v151 offset:52224
	ds_read_b128 v[200:203], v151 offset:53248
	ds_read_b128 v[204:207], v151 offset:54272
	ds_read_b128 v[208:211], v151 offset:55296
	ds_read_b128 v[212:215], v151 offset:56320
	global_load_lds_dwordx4 v[142:143], off
	v_lshl_add_u64 v[142:143], v[216:217], 0, s[34:35]
	s_add_i32 m0, s28, 0x2000
	s_add_i32 s28, s72, s18
	global_load_lds_dwordx4 v[142:143], off
	v_lshl_add_u64 v[142:143], v[218:219], 0, s[34:35]
	s_mov_b32 m0, s28
	s_nop 0
	global_load_lds_dwordx4 v[142:143], off
	v_lshl_add_u64 v[142:143], v[220:221], 0, s[34:35]
	s_add_i32 m0, s28, 0x2000
	s_nop 0
	global_load_lds_dwordx4 v[142:143], off
	v_lshl_add_u64 v[142:143], v[222:223], 0, s[34:35]
	s_mov_b32 m0, s51
	s_nop 0
	global_load_lds_dwordx4 v[142:143], off
	v_lshl_add_u64 v[142:143], v[224:225], 0, s[34:35]
	s_mov_b32 m0, s52
	s_nop 0
	global_load_lds_dwordx4 v[142:143], off
	s_add_u32 s46, s46, 0x100
	s_addc_u32 s47, s47, 0
	s_add_u32 s33, s33, 0x100
	s_addc_u32 s67, s67, 0
	s_waitcnt vmcnt(8)
	s_waitcnt lgkmcnt(0)
	s_barrier
	s_waitcnt lgkmcnt(0)
	v_mfma_f32_16x16x32_bf16 v[60:63], v[152:155], v[184:187], v[60:63]
	v_mfma_f32_16x16x32_bf16 v[56:59], v[160:163], v[184:187], v[56:59]
	v_mfma_f32_16x16x32_bf16 v[44:47], v[152:155], v[192:195], v[44:47]
	v_mfma_f32_16x16x32_bf16 v[40:43], v[160:163], v[192:195], v[40:43]
	v_mfma_f32_16x16x32_bf16 v[28:31], v[152:155], v[200:203], v[28:31]
	v_mfma_f32_16x16x32_bf16 v[24:27], v[160:163], v[200:203], v[24:27]
	v_mfma_f32_16x16x32_bf16 v[12:15], v[152:155], v[208:211], v[12:15]
	v_mfma_f32_16x16x32_bf16 v[8:11], v[160:163], v[208:211], v[8:11]
	v_mfma_f32_16x16x32_bf16 v[60:63], v[156:159], v[188:191], v[60:63]
	v_mfma_f32_16x16x32_bf16 v[56:59], v[164:167], v[188:191], v[56:59]
	v_mfma_f32_16x16x32_bf16 v[44:47], v[156:159], v[196:199], v[44:47]
	v_mfma_f32_16x16x32_bf16 v[40:43], v[164:167], v[196:199], v[40:43]
	v_mfma_f32_16x16x32_bf16 v[28:31], v[156:159], v[204:207], v[28:31]
	v_mfma_f32_16x16x32_bf16 v[24:27], v[164:167], v[204:207], v[24:27]
	v_mfma_f32_16x16x32_bf16 v[12:15], v[156:159], v[212:215], v[12:15]
	v_mfma_f32_16x16x32_bf16 v[8:11], v[164:167], v[212:215], v[8:11]
	v_mfma_f32_16x16x32_bf16 v[52:55], v[168:171], v[184:187], v[52:55]
	v_mfma_f32_16x16x32_bf16 v[48:51], v[176:179], v[184:187], v[48:51]
	v_mfma_f32_16x16x32_bf16 v[36:39], v[168:171], v[192:195], v[36:39]
	v_mfma_f32_16x16x32_bf16 v[32:35], v[176:179], v[192:195], v[32:35]
	v_mfma_f32_16x16x32_bf16 v[20:23], v[168:171], v[200:203], v[20:23]
	v_mfma_f32_16x16x32_bf16 v[16:19], v[176:179], v[200:203], v[16:19]
	v_mfma_f32_16x16x32_bf16 v[4:7], v[168:171], v[208:211], v[4:7]
	v_mfma_f32_16x16x32_bf16 v[0:3], v[176:179], v[208:211], v[0:3]
	v_mfma_f32_16x16x32_bf16 v[52:55], v[172:175], v[188:191], v[52:55]
	v_mfma_f32_16x16x32_bf16 v[48:51], v[180:183], v[188:191], v[48:51]
	v_mfma_f32_16x16x32_bf16 v[36:39], v[172:175], v[196:199], v[36:39]
	v_mfma_f32_16x16x32_bf16 v[32:35], v[180:183], v[196:199], v[32:35]
	v_mfma_f32_16x16x32_bf16 v[20:23], v[172:175], v[204:207], v[20:23]
	v_mfma_f32_16x16x32_bf16 v[16:19], v[180:183], v[204:207], v[16:19]
	v_mfma_f32_16x16x32_bf16 v[4:7], v[172:175], v[212:215], v[4:7]
	v_mfma_f32_16x16x32_bf16 v[0:3], v[180:183], v[212:215], v[0:3]
	s_barrier
	s_cmp_ge_i32 s70, s53
	s_mov_b32 s28, s70
	s_cbranch_scc0 .LBB0_1646
	s_mov_b32 s101, 1
	s_movk_i32 s76, 0x6000

.LBB0_1756:
	s_add_i32 s43, s28, 2
	s_add_u32 s46, s40, 0x80
	s_addc_u32 s29, s41, 0
	s_add_i32 s64, 0, 0x10000
	s_cmp_eq_u32 s97, s28
	s_cselect_b32 s29, s61, s29
	s_cselect_b32 s28, s60, s46
	v_add_u32_e32 v128, s64, v195
	s_cselect_b32 s47, s63, s42
	s_cselect_b32 s46, s62, s33
	s_add_i32 s65, 0, 0x14000
	ds_read_b128 v[130:133], v128
	ds_read_b128 v[134:137], v128 offset:1024
	ds_read_b128 v[138:141], v128 offset:2048
	ds_read_b128 v[142:145], v128 offset:3072
	v_add_u32_e32 v128, s65, v195
	ds_read_b128 v[164:167], v128
	s_waitcnt lgkmcnt(0)
	ds_read_b128 v[168:171], v128 offset:1024
	ds_read_b128 v[172:175], v128 offset:2048
	ds_read_b128 v[176:179], v128 offset:3072
	v_lshl_add_u64 v[192:193], s[40:41], 0, v[160:161]
	s_add_i32 m0, s7, 0xc000
	ds_read_b128 v[180:183], v202
	ds_read_b128 v[184:187], v202 offset:1024
	ds_read_b128 v[188:191], v202 offset:2048
	ds_read_b128 v[204:207], v202 offset:3072
	ds_read_b128 v[208:211], v202 offset:4096
	ds_read_b128 v[212:215], v202 offset:5120
	ds_read_b128 v[216:219], v202 offset:6144
	ds_read_b128 v[220:223], v202 offset:7168
	global_load_lds_dwordx4 v[192:193], off
	v_lshl_add_u64 v[192:193], s[40:41], 0, v[162:163]
	s_add_i32 m0, s7, 0xe000
	s_nop 0
	global_load_lds_dwordx4 v[192:193], off
	s_waitcnt vmcnt(8)
	s_waitcnt lgkmcnt(0)
	s_barrier
	s_waitcnt lgkmcnt(0)
	v_mfma_f32_16x16x32_bf16 v[112:115], v[130:133], v[180:183], v[112:115]
	v_mfma_f32_16x16x32_bf16 v[124:127], v[138:141], v[180:183], v[124:127]
	v_mfma_f32_16x16x32_bf16 v[100:103], v[130:133], v[188:191], v[100:103]
	v_mfma_f32_16x16x32_bf16 v[108:111], v[138:141], v[188:191], v[108:111]
	v_mfma_f32_16x16x32_bf16 v[84:87], v[130:133], v[208:211], v[84:87]
	v_mfma_f32_16x16x32_bf16 v[92:95], v[138:141], v[208:211], v[92:95]
	v_mfma_f32_16x16x32_bf16 v[68:71], v[130:133], v[216:219], v[68:71]
	v_mfma_f32_16x16x32_bf16 v[76:79], v[138:141], v[216:219], v[76:79]
	v_mfma_f32_16x16x32_bf16 v[112:115], v[134:137], v[184:187], v[112:115]
	v_mfma_f32_16x16x32_bf16 v[124:127], v[142:145], v[184:187], v[124:127]
	v_mfma_f32_16x16x32_bf16 v[100:103], v[134:137], v[204:207], v[100:103]
	v_mfma_f32_16x16x32_bf16 v[108:111], v[142:145], v[204:207], v[108:111]
	v_mfma_f32_16x16x32_bf16 v[84:87], v[134:137], v[212:215], v[84:87]
	v_mfma_f32_16x16x32_bf16 v[92:95], v[142:145], v[212:215], v[92:95]
	v_mfma_f32_16x16x32_bf16 v[68:71], v[134:137], v[220:223], v[68:71]
	v_mfma_f32_16x16x32_bf16 v[76:79], v[142:145], v[220:223], v[76:79]
	v_mfma_f32_16x16x32_bf16 v[116:119], v[164:167], v[180:183], v[116:119]
	v_mfma_f32_16x16x32_bf16 v[120:123], v[172:175], v[180:183], v[120:123]
	v_mfma_f32_16x16x32_bf16 v[96:99], v[164:167], v[188:191], v[96:99]
	v_mfma_f32_16x16x32_bf16 v[104:107], v[172:175], v[188:191], v[104:107]
	v_mfma_f32_16x16x32_bf16 v[80:83], v[164:167], v[208:211], v[80:83]
	v_mfma_f32_16x16x32_bf16 v[88:91], v[172:175], v[208:211], v[88:91]
	v_mfma_f32_16x16x32_bf16 v[64:67], v[164:167], v[216:219], v[64:67]
	v_mfma_f32_16x16x32_bf16 v[72:75], v[172:175], v[216:219], v[72:75]
	v_mfma_f32_16x16x32_bf16 v[116:119], v[168:171], v[184:187], v[116:119]
	v_mfma_f32_16x16x32_bf16 v[120:123], v[176:179], v[184:187], v[120:123]
	v_mfma_f32_16x16x32_bf16 v[96:99], v[168:171], v[204:207], v[96:99]
	v_mfma_f32_16x16x32_bf16 v[104:107], v[176:179], v[204:207], v[104:107]
	v_mfma_f32_16x16x32_bf16 v[80:83], v[168:171], v[212:215], v[80:83]
	v_mfma_f32_16x16x32_bf16 v[88:91], v[176:179], v[212:215], v[88:91]
	v_mfma_f32_16x16x32_bf16 v[64:67], v[168:171], v[220:223], v[64:67]
	v_mfma_f32_16x16x32_bf16 v[72:75], v[176:179], v[220:223], v[72:75]
	s_barrier
	s_add_i32 s64, s64, s4
	v_lshl_add_u64 v[192:193], s[46:47], 0, v[150:151]
	s_mov_b32 m0, s64
	ds_read_b128 v[180:183], v202 offset:16384
	ds_read_b128 v[184:187], v202 offset:17408
	ds_read_b128 v[188:191], v202 offset:18432
	ds_read_b128 v[204:207], v202 offset:19456
	ds_read_b128 v[208:211], v202 offset:20480
	ds_read_b128 v[212:215], v202 offset:21504
	ds_read_b128 v[216:219], v202 offset:22528
	ds_read_b128 v[220:223], v202 offset:23552
	global_load_lds_dwordx4 v[192:193], off
	s_add_i32 m0, s64, 0x2000
	v_lshl_add_u64 v[198:199], s[46:47], 0, v[154:155]
	s_add_u32 s46, s46, s14
	s_addc_u32 s47, s47, s15
	s_add_i32 s64, s65, s4
	global_load_lds_dwordx4 v[198:199], off
	v_lshl_add_u64 v[200:201], s[46:47], 0, v[150:151]
	s_mov_b32 m0, s64
	v_lshl_add_u64 v[224:225], s[46:47], 0, v[154:155]
	global_load_lds_dwordx4 v[200:201], off
	s_add_i32 m0, s64, 0x2000
	v_lshl_add_u64 v[226:227], s[28:29], 0, v[148:149]
	global_load_lds_dwordx4 v[224:225], off
	s_mov_b32 m0, s7
	v_lshl_add_u64 v[228:229], s[28:29], 0, v[152:153]
	global_load_lds_dwordx4 v[226:227], off
	s_mov_b32 m0, s48
	s_nop 0
	global_load_lds_dwordx4 v[228:229], off
	s_waitcnt vmcnt(8)
	s_waitcnt lgkmcnt(0)
	s_barrier
	s_waitcnt lgkmcnt(0)
	v_mfma_f32_16x16x32_bf16 v[52:55], v[130:133], v[180:183], v[52:55]
	v_mfma_f32_16x16x32_bf16 v[60:63], v[138:141], v[180:183], v[60:63]
	v_mfma_f32_16x16x32_bf16 v[36:39], v[130:133], v[188:191], v[36:39]
	v_mfma_f32_16x16x32_bf16 v[44:47], v[138:141], v[188:191], v[44:47]
	v_mfma_f32_16x16x32_bf16 v[20:23], v[130:133], v[208:211], v[20:23]
	v_mfma_f32_16x16x32_bf16 v[28:31], v[138:141], v[208:211], v[28:31]
	v_mfma_f32_16x16x32_bf16 v[12:15], v[130:133], v[216:219], v[12:15]
	v_mfma_f32_16x16x32_bf16 v[4:7], v[138:141], v[216:219], v[4:7]
	v_mfma_f32_16x16x32_bf16 v[52:55], v[134:137], v[184:187], v[52:55]
	v_mfma_f32_16x16x32_bf16 v[60:63], v[142:145], v[184:187], v[60:63]
	v_mfma_f32_16x16x32_bf16 v[36:39], v[134:137], v[204:207], v[36:39]
	v_mfma_f32_16x16x32_bf16 v[44:47], v[142:145], v[204:207], v[44:47]
	v_mfma_f32_16x16x32_bf16 v[20:23], v[134:137], v[212:215], v[20:23]
	v_mfma_f32_16x16x32_bf16 v[28:31], v[142:145], v[212:215], v[28:31]
	v_mfma_f32_16x16x32_bf16 v[12:15], v[134:137], v[220:223], v[12:15]
	v_mfma_f32_16x16x32_bf16 v[4:7], v[142:145], v[220:223], v[4:7]
	v_mfma_f32_16x16x32_bf16 v[48:51], v[164:167], v[180:183], v[48:51]
	v_mfma_f32_16x16x32_bf16 v[56:59], v[172:175], v[180:183], v[56:59]
	v_mfma_f32_16x16x32_bf16 v[32:35], v[164:167], v[188:191], v[32:35]
	v_mfma_f32_16x16x32_bf16 v[40:43], v[172:175], v[188:191], v[40:43]
	v_mfma_f32_16x16x32_bf16 v[16:19], v[164:167], v[208:211], v[16:19]
	v_mfma_f32_16x16x32_bf16 v[24:27], v[172:175], v[208:211], v[24:27]
	v_mfma_f32_16x16x32_bf16 v[8:11], v[164:167], v[216:219], v[8:11]
	v_mfma_f32_16x16x32_bf16 v[0:3], v[172:175], v[216:219], v[0:3]
	v_mfma_f32_16x16x32_bf16 v[48:51], v[168:171], v[184:187], v[48:51]
	v_mfma_f32_16x16x32_bf16 v[56:59], v[176:179], v[184:187], v[56:59]
	v_mfma_f32_16x16x32_bf16 v[32:35], v[168:171], v[204:207], v[32:35]
	v_mfma_f32_16x16x32_bf16 v[40:43], v[176:179], v[204:207], v[40:43]
	v_mfma_f32_16x16x32_bf16 v[16:19], v[168:171], v[212:215], v[16:19]
	v_mfma_f32_16x16x32_bf16 v[24:27], v[176:179], v[212:215], v[24:27]
	v_mfma_f32_16x16x32_bf16 v[8:11], v[168:171], v[220:223], v[8:11]
	v_mfma_f32_16x16x32_bf16 v[0:3], v[176:179], v[220:223], v[0:3]
	s_barrier
	s_add_i32 s46, 0, 0x18000
	v_add_u32_e32 v128, s46, v195
	s_add_i32 s47, 0, 0x1c000
	ds_read_b128 v[130:133], v128
	ds_read_b128 v[134:137], v128 offset:1024
	ds_read_b128 v[138:141], v128 offset:2048
	ds_read_b128 v[142:145], v128 offset:3072
	v_add_u32_e32 v128, s47, v195
	ds_read_b128 v[164:167], v128
	ds_read_b128 v[168:171], v128 offset:1024
	ds_read_b128 v[172:175], v128 offset:2048
	ds_read_b128 v[176:179], v128 offset:3072
	s_add_u32 s28, s28, s14
	s_addc_u32 s29, s29, s15
	s_mov_b32 m0, s49
	v_lshl_add_u64 v[230:231], s[28:29], 0, v[148:149]
	ds_read_b128 v[180:183], v202 offset:32768
	ds_read_b128 v[184:187], v202 offset:33792
	ds_read_b128 v[188:191], v202 offset:34816
	ds_read_b128 v[204:207], v202 offset:35840
	ds_read_b128 v[208:211], v202 offset:36864
	ds_read_b128 v[212:215], v202 offset:37888
	ds_read_b128 v[216:219], v202 offset:38912
	ds_read_b128 v[220:223], v202 offset:39936
	global_load_lds_dwordx4 v[230:231], off
	v_lshl_add_u64 v[230:231], s[28:29], 0, v[152:153]
	s_mov_b32 m0, s89
	s_nop 0
	global_load_lds_dwordx4 v[230:231], off
	s_waitcnt vmcnt(8)
	s_waitcnt lgkmcnt(0)
	s_barrier
	s_waitcnt lgkmcnt(0)
	v_mfma_f32_16x16x32_bf16 v[112:115], v[130:133], v[180:183], v[112:115]
	v_mfma_f32_16x16x32_bf16 v[124:127], v[138:141], v[180:183], v[124:127]
	v_mfma_f32_16x16x32_bf16 v[100:103], v[130:133], v[188:191], v[100:103]
	v_mfma_f32_16x16x32_bf16 v[108:111], v[138:141], v[188:191], v[108:111]
	v_mfma_f32_16x16x32_bf16 v[84:87], v[130:133], v[208:211], v[84:87]
	v_mfma_f32_16x16x32_bf16 v[92:95], v[138:141], v[208:211], v[92:95]
	v_mfma_f32_16x16x32_bf16 v[68:71], v[130:133], v[216:219], v[68:71]
	v_mfma_f32_16x16x32_bf16 v[76:79], v[138:141], v[216:219], v[76:79]
	v_mfma_f32_16x16x32_bf16 v[112:115], v[134:137], v[184:187], v[112:115]
	v_mfma_f32_16x16x32_bf16 v[124:127], v[142:145], v[184:187], v[124:127]
	v_mfma_f32_16x16x32_bf16 v[100:103], v[134:137], v[204:207], v[100:103]
	v_mfma_f32_16x16x32_bf16 v[108:111], v[142:145], v[204:207], v[108:111]
	v_mfma_f32_16x16x32_bf16 v[84:87], v[134:137], v[212:215], v[84:87]
	v_mfma_f32_16x16x32_bf16 v[92:95], v[142:145], v[212:215], v[92:95]
	v_mfma_f32_16x16x32_bf16 v[68:71], v[134:137], v[220:223], v[68:71]
	v_mfma_f32_16x16x32_bf16 v[76:79], v[142:145], v[220:223], v[76:79]
	v_mfma_f32_16x16x32_bf16 v[116:119], v[164:167], v[180:183], v[116:119]
	v_mfma_f32_16x16x32_bf16 v[120:123], v[172:175], v[180:183], v[120:123]
	v_mfma_f32_16x16x32_bf16 v[96:99], v[164:167], v[188:191], v[96:99]
	v_mfma_f32_16x16x32_bf16 v[104:107], v[172:175], v[188:191], v[104:107]
	v_mfma_f32_16x16x32_bf16 v[80:83], v[164:167], v[208:211], v[80:83]
	v_mfma_f32_16x16x32_bf16 v[88:91], v[172:175], v[208:211], v[88:91]
	v_mfma_f32_16x16x32_bf16 v[64:67], v[164:167], v[216:219], v[64:67]
	v_mfma_f32_16x16x32_bf16 v[72:75], v[172:175], v[216:219], v[72:75]
	v_mfma_f32_16x16x32_bf16 v[116:119], v[168:171], v[184:187], v[116:119]
	v_mfma_f32_16x16x32_bf16 v[120:123], v[176:179], v[184:187], v[120:123]
	v_mfma_f32_16x16x32_bf16 v[96:99], v[168:171], v[204:207], v[96:99]
	v_mfma_f32_16x16x32_bf16 v[104:107], v[176:179], v[204:207], v[104:107]
	v_mfma_f32_16x16x32_bf16 v[80:83], v[168:171], v[212:215], v[80:83]
	v_mfma_f32_16x16x32_bf16 v[88:91], v[176:179], v[212:215], v[88:91]
	v_mfma_f32_16x16x32_bf16 v[64:67], v[168:171], v[220:223], v[64:67]
	v_mfma_f32_16x16x32_bf16 v[72:75], v[176:179], v[220:223], v[72:75]
	s_barrier
	s_add_i32 s28, s46, s4
	v_lshl_add_u64 v[192:193], v[192:193], 0, s[34:35]
	s_mov_b32 m0, s28
	ds_read_b128 v[180:183], v202 offset:49152
	ds_read_b128 v[184:187], v202 offset:50176
	ds_read_b128 v[188:191], v202 offset:51200
	ds_read_b128 v[204:207], v202 offset:52224
	ds_read_b128 v[208:211], v202 offset:53248
	ds_read_b128 v[212:215], v202 offset:54272
	ds_read_b128 v[216:219], v202 offset:55296
	ds_read_b128 v[220:223], v202 offset:56320
	global_load_lds_dwordx4 v[192:193], off
	v_lshl_add_u64 v[192:193], v[198:199], 0, s[34:35]
	s_add_i32 m0, s28, 0x2000
	s_add_i32 s28, s47, s4
	global_load_lds_dwordx4 v[192:193], off
	v_lshl_add_u64 v[192:193], v[200:201], 0, s[34:35]
	s_mov_b32 m0, s28
	s_nop 0
	global_load_lds_dwordx4 v[192:193], off
	v_lshl_add_u64 v[192:193], v[224:225], 0, s[34:35]
	s_add_i32 m0, s28, 0x2000
	s_nop 0
	global_load_lds_dwordx4 v[192:193], off
	v_lshl_add_u64 v[192:193], v[226:227], 0, s[34:35]
	s_mov_b32 m0, s95
	s_nop 0
	global_load_lds_dwordx4 v[192:193], off
	v_lshl_add_u64 v[192:193], v[228:229], 0, s[34:35]
	s_mov_b32 m0, s96
	s_nop 0
	global_load_lds_dwordx4 v[192:193], off
	s_add_u32 s40, s40, 0x100
	s_addc_u32 s41, s41, 0
	s_add_u32 s33, s33, 0x100
	s_addc_u32 s42, s42, 0
	s_waitcnt vmcnt(8)
	s_waitcnt lgkmcnt(0)
	s_barrier
	s_waitcnt lgkmcnt(0)
	v_mfma_f32_16x16x32_bf16 v[52:55], v[130:133], v[180:183], v[52:55]
	v_mfma_f32_16x16x32_bf16 v[60:63], v[138:141], v[180:183], v[60:63]
	v_mfma_f32_16x16x32_bf16 v[36:39], v[130:133], v[188:191], v[36:39]
	v_mfma_f32_16x16x32_bf16 v[44:47], v[138:141], v[188:191], v[44:47]
	v_mfma_f32_16x16x32_bf16 v[20:23], v[130:133], v[208:211], v[20:23]
	v_mfma_f32_16x16x32_bf16 v[28:31], v[138:141], v[208:211], v[28:31]
	v_mfma_f32_16x16x32_bf16 v[12:15], v[130:133], v[216:219], v[12:15]
	v_mfma_f32_16x16x32_bf16 v[4:7], v[138:141], v[216:219], v[4:7]
	v_mfma_f32_16x16x32_bf16 v[52:55], v[134:137], v[184:187], v[52:55]
	v_mfma_f32_16x16x32_bf16 v[60:63], v[142:145], v[184:187], v[60:63]
	v_mfma_f32_16x16x32_bf16 v[36:39], v[134:137], v[204:207], v[36:39]
	v_mfma_f32_16x16x32_bf16 v[44:47], v[142:145], v[204:207], v[44:47]
	v_mfma_f32_16x16x32_bf16 v[20:23], v[134:137], v[212:215], v[20:23]
	v_mfma_f32_16x16x32_bf16 v[28:31], v[142:145], v[212:215], v[28:31]
	v_mfma_f32_16x16x32_bf16 v[12:15], v[134:137], v[220:223], v[12:15]
	v_mfma_f32_16x16x32_bf16 v[4:7], v[142:145], v[220:223], v[4:7]
	v_mfma_f32_16x16x32_bf16 v[48:51], v[164:167], v[180:183], v[48:51]
	v_mfma_f32_16x16x32_bf16 v[56:59], v[172:175], v[180:183], v[56:59]
	v_mfma_f32_16x16x32_bf16 v[32:35], v[164:167], v[188:191], v[32:35]
	v_mfma_f32_16x16x32_bf16 v[40:43], v[172:175], v[188:191], v[40:43]
	v_mfma_f32_16x16x32_bf16 v[16:19], v[164:167], v[208:211], v[16:19]
	v_mfma_f32_16x16x32_bf16 v[24:27], v[172:175], v[208:211], v[24:27]
	v_mfma_f32_16x16x32_bf16 v[8:11], v[164:167], v[216:219], v[8:11]
	v_mfma_f32_16x16x32_bf16 v[0:3], v[172:175], v[216:219], v[0:3]
	v_mfma_f32_16x16x32_bf16 v[48:51], v[168:171], v[184:187], v[48:51]
	v_mfma_f32_16x16x32_bf16 v[56:59], v[176:179], v[184:187], v[56:59]
	v_mfma_f32_16x16x32_bf16 v[32:35], v[168:171], v[204:207], v[32:35]
	v_mfma_f32_16x16x32_bf16 v[40:43], v[176:179], v[204:207], v[40:43]
	v_mfma_f32_16x16x32_bf16 v[16:19], v[168:171], v[212:215], v[16:19]
	v_mfma_f32_16x16x32_bf16 v[24:27], v[176:179], v[212:215], v[24:27]
	v_mfma_f32_16x16x32_bf16 v[8:11], v[168:171], v[220:223], v[8:11]
	v_mfma_f32_16x16x32_bf16 v[0:3], v[176:179], v[220:223], v[0:3]
	s_barrier
	s_cmp_ge_i32 s43, s91
	s_mov_b32 s28, s43
	s_cbranch_scc0 .LBB0_1756

.Lrx_join_2319_1:
	s_mov_b32 s101, 0
	s_waitcnt lgkmcnt(0)
	s_barrier
	s_waitcnt lgkmcnt(0)
	v_mfma_f32_16x16x32_bf16 v[60:63], v[142:145], v[186:189], v[60:63]
	v_mfma_f32_16x16x32_bf16 v[56:59], v[162:165], v[186:189], v[56:59]
	v_mfma_f32_16x16x32_bf16 v[44:47], v[142:145], v[194:197], v[44:47]
	v_mfma_f32_16x16x32_bf16 v[40:43], v[162:165], v[194:197], v[40:43]
	v_mfma_f32_16x16x32_bf16 v[28:31], v[142:145], v[202:205], v[28:31]
	v_mfma_f32_16x16x32_bf16 v[24:27], v[162:165], v[202:205], v[24:27]
	v_mfma_f32_16x16x32_bf16 v[12:15], v[142:145], v[210:213], v[12:15]
	v_mfma_f32_16x16x32_bf16 v[8:11], v[162:165], v[210:213], v[8:11]
	v_mfma_f32_16x16x32_bf16 v[60:63], v[146:149], v[190:193], v[60:63]
	v_mfma_f32_16x16x32_bf16 v[56:59], v[166:169], v[190:193], v[56:59]
	v_mfma_f32_16x16x32_bf16 v[44:47], v[146:149], v[198:201], v[44:47]
	v_mfma_f32_16x16x32_bf16 v[40:43], v[166:169], v[198:201], v[40:43]
	v_mfma_f32_16x16x32_bf16 v[28:31], v[146:149], v[206:209], v[28:31]
	v_mfma_f32_16x16x32_bf16 v[24:27], v[166:169], v[206:209], v[24:27]
	v_mfma_f32_16x16x32_bf16 v[12:15], v[146:149], v[214:217], v[12:15]
	v_mfma_f32_16x16x32_bf16 v[8:11], v[166:169], v[214:217], v[8:11]
	v_mfma_f32_16x16x32_bf16 v[52:55], v[170:173], v[186:189], v[52:55]
	v_mfma_f32_16x16x32_bf16 v[48:51], v[178:181], v[186:189], v[48:51]
	v_mfma_f32_16x16x32_bf16 v[36:39], v[170:173], v[194:197], v[36:39]
	v_mfma_f32_16x16x32_bf16 v[32:35], v[178:181], v[194:197], v[32:35]
	v_mfma_f32_16x16x32_bf16 v[20:23], v[170:173], v[202:205], v[20:23]
	v_mfma_f32_16x16x32_bf16 v[16:19], v[178:181], v[202:205], v[16:19]
	v_mfma_f32_16x16x32_bf16 v[4:7], v[170:173], v[210:213], v[4:7]
	v_mfma_f32_16x16x32_bf16 v[0:3], v[178:181], v[210:213], v[0:3]
	v_mfma_f32_16x16x32_bf16 v[52:55], v[174:177], v[190:193], v[52:55]
	v_mfma_f32_16x16x32_bf16 v[48:51], v[182:185], v[190:193], v[48:51]
	v_mfma_f32_16x16x32_bf16 v[36:39], v[174:177], v[198:201], v[36:39]
	v_mfma_f32_16x16x32_bf16 v[32:35], v[182:185], v[198:201], v[32:35]
	v_mfma_f32_16x16x32_bf16 v[20:23], v[174:177], v[206:209], v[20:23]
	v_mfma_f32_16x16x32_bf16 v[16:19], v[182:185], v[206:209], v[16:19]
	v_mfma_f32_16x16x32_bf16 v[4:7], v[174:177], v[214:217], v[4:7]
	v_mfma_f32_16x16x32_bf16 v[0:3], v[182:185], v[214:217], v[0:3]
	s_barrier
	s_add_i32 s65, 0, 0x18000
	v_add_u32_e32 v161, s65, v153
	s_add_i32 s67, 0, 0x1c000
	ds_read_b128 v[142:145], v161
	ds_read_b128 v[146:149], v161 offset:1024
	ds_read_b128 v[162:165], v161 offset:2048
	ds_read_b128 v[166:169], v161 offset:3072
	v_add_u32_e32 v161, s67, v153
	ds_read_b128 v[170:173], v161
	ds_read_b128 v[174:177], v161 offset:1024
	ds_read_b128 v[178:181], v161 offset:2048
	ds_read_b128 v[182:185], v161 offset:3072
	s_add_u32 s28, s28, s22
	s_addc_u32 s29, s29, s23
	s_mov_b32 m0, s50
	v_lshl_add_u64 v[230:231], s[28:29], 0, v[132:133]
	ds_read_b128 v[186:189], v160 offset:32768
	ds_read_b128 v[190:193], v160 offset:33792
	ds_read_b128 v[194:197], v160 offset:34816
	ds_read_b128 v[198:201], v160 offset:35840
	ds_read_b128 v[202:205], v160 offset:36864
	ds_read_b128 v[206:209], v160 offset:37888
	ds_read_b128 v[210:213], v160 offset:38912
	ds_read_b128 v[214:217], v160 offset:39936
	global_load_lds_dwordx4 v[230:231], off
	v_lshl_add_u64 v[230:231], s[28:29], 0, v[134:135]
	s_mov_b32 m0, s51
	s_nop 0
	global_load_lds_dwordx4 v[230:231], off
	s_waitcnt vmcnt(8)
	s_waitcnt lgkmcnt(0)
	s_barrier
	s_waitcnt lgkmcnt(0)
	v_mfma_f32_16x16x32_bf16 v[124:127], v[142:145], v[186:189], v[124:127]
	v_mfma_f32_16x16x32_bf16 v[120:123], v[162:165], v[186:189], v[120:123]
	v_mfma_f32_16x16x32_bf16 v[108:111], v[142:145], v[194:197], v[108:111]
	v_mfma_f32_16x16x32_bf16 v[104:107], v[162:165], v[194:197], v[104:107]
	v_mfma_f32_16x16x32_bf16 v[92:95], v[142:145], v[202:205], v[92:95]
	v_mfma_f32_16x16x32_bf16 v[88:91], v[162:165], v[202:205], v[88:91]
	v_mfma_f32_16x16x32_bf16 v[76:79], v[142:145], v[210:213], v[76:79]
	v_mfma_f32_16x16x32_bf16 v[72:75], v[162:165], v[210:213], v[72:75]
	v_mfma_f32_16x16x32_bf16 v[124:127], v[146:149], v[190:193], v[124:127]
	v_mfma_f32_16x16x32_bf16 v[120:123], v[166:169], v[190:193], v[120:123]
	v_mfma_f32_16x16x32_bf16 v[108:111], v[146:149], v[198:201], v[108:111]
	v_mfma_f32_16x16x32_bf16 v[104:107], v[166:169], v[198:201], v[104:107]
	v_mfma_f32_16x16x32_bf16 v[92:95], v[146:149], v[206:209], v[92:95]
	v_mfma_f32_16x16x32_bf16 v[88:91], v[166:169], v[206:209], v[88:91]
	v_mfma_f32_16x16x32_bf16 v[76:79], v[146:149], v[214:217], v[76:79]
	v_mfma_f32_16x16x32_bf16 v[72:75], v[166:169], v[214:217], v[72:75]
	v_mfma_f32_16x16x32_bf16 v[116:119], v[170:173], v[186:189], v[116:119]
	v_mfma_f32_16x16x32_bf16 v[112:115], v[178:181], v[186:189], v[112:115]
	v_mfma_f32_16x16x32_bf16 v[100:103], v[170:173], v[194:197], v[100:103]
	v_mfma_f32_16x16x32_bf16 v[96:99], v[178:181], v[194:197], v[96:99]
	v_mfma_f32_16x16x32_bf16 v[84:87], v[170:173], v[202:205], v[84:87]
	v_mfma_f32_16x16x32_bf16 v[80:83], v[178:181], v[202:205], v[80:83]
	v_mfma_f32_16x16x32_bf16 v[68:71], v[170:173], v[210:213], v[68:71]
	v_mfma_f32_16x16x32_bf16 v[64:67], v[178:181], v[210:213], v[64:67]
	v_mfma_f32_16x16x32_bf16 v[116:119], v[174:177], v[190:193], v[116:119]
	v_mfma_f32_16x16x32_bf16 v[112:115], v[182:185], v[190:193], v[112:115]
	v_mfma_f32_16x16x32_bf16 v[100:103], v[174:177], v[198:201], v[100:103]
	v_mfma_f32_16x16x32_bf16 v[96:99], v[182:185], v[198:201], v[96:99]
	v_mfma_f32_16x16x32_bf16 v[84:87], v[174:177], v[206:209], v[84:87]
	v_mfma_f32_16x16x32_bf16 v[80:83], v[182:185], v[206:209], v[80:83]
	v_mfma_f32_16x16x32_bf16 v[68:71], v[174:177], v[214:217], v[68:71]
	v_mfma_f32_16x16x32_bf16 v[64:67], v[182:185], v[214:217], v[64:67]
	s_barrier
	s_add_i32 s28, s65, s6
	v_lshl_add_u64 v[218:219], v[218:219], 0, s[34:35]
	s_mov_b32 m0, s28
	ds_read_b128 v[186:189], v160 offset:49152
	ds_read_b128 v[190:193], v160 offset:50176
	ds_read_b128 v[194:197], v160 offset:51200
	ds_read_b128 v[198:201], v160 offset:52224
	ds_read_b128 v[202:205], v160 offset:53248
	ds_read_b128 v[206:209], v160 offset:54272
	ds_read_b128 v[210:213], v160 offset:55296
	ds_read_b128 v[214:217], v160 offset:56320
	global_load_lds_dwordx4 v[218:219], off
	v_lshl_add_u64 v[218:219], v[220:221], 0, s[34:35]
	s_add_i32 m0, s28, 0x2000
	s_add_i32 s28, s67, s6
	global_load_lds_dwordx4 v[218:219], off
	v_lshl_add_u64 v[218:219], v[222:223], 0, s[34:35]
	s_mov_b32 m0, s28
	s_nop 0
	global_load_lds_dwordx4 v[218:219], off
	v_lshl_add_u64 v[218:219], v[224:225], 0, s[34:35]
	s_add_i32 m0, s28, 0x2000
	s_nop 0
	global_load_lds_dwordx4 v[218:219], off
	v_lshl_add_u64 v[218:219], v[226:227], 0, s[34:35]
	s_mov_b32 m0, s52
	s_nop 0
	global_load_lds_dwordx4 v[218:219], off
	v_lshl_add_u64 v[218:219], v[228:229], 0, s[34:35]
	s_mov_b32 m0, s53
	s_nop 0
	global_load_lds_dwordx4 v[218:219], off
	s_add_u32 s46, s46, 0x100
	s_addc_u32 s47, s47, 0
	s_add_u32 s33, s33, 0x100
	s_addc_u32 s63, s63, 0
	s_waitcnt vmcnt(8)
	s_waitcnt lgkmcnt(0)
	s_barrier
	s_waitcnt lgkmcnt(0)
	v_mfma_f32_16x16x32_bf16 v[60:63], v[142:145], v[186:189], v[60:63]
	v_mfma_f32_16x16x32_bf16 v[56:59], v[162:165], v[186:189], v[56:59]
	v_mfma_f32_16x16x32_bf16 v[44:47], v[142:145], v[194:197], v[44:47]
	v_mfma_f32_16x16x32_bf16 v[40:43], v[162:165], v[194:197], v[40:43]
	v_mfma_f32_16x16x32_bf16 v[28:31], v[142:145], v[202:205], v[28:31]
	v_mfma_f32_16x16x32_bf16 v[24:27], v[162:165], v[202:205], v[24:27]
	v_mfma_f32_16x16x32_bf16 v[12:15], v[142:145], v[210:213], v[12:15]
	v_mfma_f32_16x16x32_bf16 v[8:11], v[162:165], v[210:213], v[8:11]
	v_mfma_f32_16x16x32_bf16 v[60:63], v[146:149], v[190:193], v[60:63]
	v_mfma_f32_16x16x32_bf16 v[56:59], v[166:169], v[190:193], v[56:59]
	v_mfma_f32_16x16x32_bf16 v[44:47], v[146:149], v[198:201], v[44:47]
	v_mfma_f32_16x16x32_bf16 v[40:43], v[166:169], v[198:201], v[40:43]
	v_mfma_f32_16x16x32_bf16 v[28:31], v[146:149], v[206:209], v[28:31]
	v_mfma_f32_16x16x32_bf16 v[24:27], v[166:169], v[206:209], v[24:27]
	v_mfma_f32_16x16x32_bf16 v[12:15], v[146:149], v[214:217], v[12:15]
	v_mfma_f32_16x16x32_bf16 v[8:11], v[166:169], v[214:217], v[8:11]
	v_mfma_f32_16x16x32_bf16 v[52:55], v[170:173], v[186:189], v[52:55]
	v_mfma_f32_16x16x32_bf16 v[48:51], v[178:181], v[186:189], v[48:51]
	v_mfma_f32_16x16x32_bf16 v[36:39], v[170:173], v[194:197], v[36:39]
	v_mfma_f32_16x16x32_bf16 v[32:35], v[178:181], v[194:197], v[32:35]
	v_mfma_f32_16x16x32_bf16 v[20:23], v[170:173], v[202:205], v[20:23]
	v_mfma_f32_16x16x32_bf16 v[16:19], v[178:181], v[202:205], v[16:19]
	v_mfma_f32_16x16x32_bf16 v[4:7], v[170:173], v[210:213], v[4:7]
	v_mfma_f32_16x16x32_bf16 v[0:3], v[178:181], v[210:213], v[0:3]
	v_mfma_f32_16x16x32_bf16 v[52:55], v[174:177], v[190:193], v[52:55]
	v_mfma_f32_16x16x32_bf16 v[48:51], v[182:185], v[190:193], v[48:51]
	v_mfma_f32_16x16x32_bf16 v[36:39], v[174:177], v[198:201], v[36:39]
	v_mfma_f32_16x16x32_bf16 v[32:35], v[182:185], v[198:201], v[32:35]
	v_mfma_f32_16x16x32_bf16 v[20:23], v[174:177], v[206:209], v[20:23]
	v_mfma_f32_16x16x32_bf16 v[16:19], v[182:185], v[206:209], v[16:19]
	v_mfma_f32_16x16x32_bf16 v[4:7], v[174:177], v[214:217], v[4:7]
	v_mfma_f32_16x16x32_bf16 v[0:3], v[182:185], v[214:217], v[0:3]
	s_barrier
	s_cmp_ge_i32 s64, s20
	s_mov_b32 s28, s64
	s_cbranch_scc0 .LBB0_2319
